# P4 softmax row-max: ds_bpermute xor16/xor32 round trips replaced by v_permlane16_swap/v_permlane32_swap (8 sites); max(x,x) canonicalisations removed; topk starts at bit 29
# speedup vs baseline: 1.0669x; 1.0116x over previous
.LBB0_429:
	s_or_b64 exec, exec, s[18:19]
	v_max_f32_e32 v1, v36, v37
	v_max_f32_e32 v2, v38, v39
	v_max3_f32 v1, v1, v2, s82
	v_max_f32_e32 v2, v26, v27
	v_max_f32_e32 v16, v22, v23
	v_max3_f32 v2, v24, v25, v2
	v_max3_f32 v16, v20, v21, v16
	v_max3_f32 v1, v1, v2, v16
	v_max_f32_e32 v2, v14, v15
	v_max3_f32 v2, v12, v13, v2
	v_max3_f32 v1, v76, v1, v2
	v_sub_f32_e32 v2, v36, v1
	v_sub_f32_e32 v16, v37, v1
	v_sub_f32_e32 v17, v38, v1
	v_sub_f32_e32 v18, v39, v1
	v_sub_f32_e32 v19, v24, v1
	v_sub_f32_e32 v28, v25, v1
	v_sub_f32_e32 v29, v26, v1
	v_sub_f32_e32 v30, v27, v1
	v_sub_f32_e32 v31, v20, v1
	v_sub_f32_e32 v77, v21, v1
	v_sub_f32_e32 v78, v22, v1
	v_sub_f32_e32 v79, v23, v1
	v_sub_f32_e32 v80, v12, v1
	v_sub_f32_e32 v81, v13, v1
	v_sub_f32_e32 v82, v14, v1
	v_sub_f32_e32 v83, v15, v1
	v_exp_f32_e32 v43, v2
	v_exp_f32_e32 v42, v16
	v_exp_f32_e32 v41, v17
	v_exp_f32_e32 v40, v18
	v_exp_f32_e32 v35, v19
	v_exp_f32_e32 v34, v28
	v_exp_f32_e32 v33, v29
	v_exp_f32_e32 v32, v30
	v_exp_f32_e32 v31, v31
	v_exp_f32_e32 v30, v77
	v_exp_f32_e32 v29, v78
	v_exp_f32_e32 v28, v79
	v_exp_f32_e32 v19, v80
	v_exp_f32_e32 v18, v81
	v_exp_f32_e32 v17, v82
	v_exp_f32_e32 v16, v83
	s_and_saveexec_b64 s[0:1], vcc
	s_xor_b64 s[0:1], exec, s[0:1]
	s_cbranch_execz .LBB0_431
	v_add_f32_e32 v2, 0, v43
	v_add_f32_e32 v2, v42, v2
	v_add_f32_e32 v2, v41, v2
	v_add_f32_e32 v2, v40, v2
	v_add_f32_e32 v2, v35, v2
	v_add_f32_e32 v2, v34, v2
	v_add_f32_e32 v2, v33, v2
	v_add_f32_e32 v2, v32, v2
	v_add_f32_e32 v2, v31, v2
	v_add_f32_e32 v2, v30, v2
	v_add_f32_e32 v2, v29, v2
	v_add_f32_e32 v2, v28, v2
	v_add_f32_e32 v2, v19, v2
	v_add_f32_e32 v2, v18, v2
	v_add_f32_e32 v2, v17, v2
	v_add_f32_e32 v2, v16, v2

.LBB0_436:
	s_or_b64 exec, exec, s[20:21]
	v_max_f32_e32 v3, v76, v77
	v_max_f32_e32 v56, v78, v79
	v_max3_f32 v3, v3, v56, s82
	v_max_f32_e32 v56, v54, v55
	v_max_f32_e32 v57, v50, v51
	v_max3_f32 v56, v52, v53, v56
	v_max3_f32 v57, v48, v49, v57
	v_max3_f32 v3, v3, v56, v57
	v_max_f32_e32 v56, v46, v47
	v_max3_f32 v56, v44, v45, v56
	v_max3_f32 v3, v1, v3, v56
	v_sub_f32_e32 v56, v76, v3
	v_sub_f32_e32 v57, v77, v3
	v_sub_f32_e32 v58, v78, v3
	v_sub_f32_e32 v59, v79, v3
	v_sub_f32_e32 v60, v52, v3
	v_sub_f32_e32 v61, v53, v3
	v_sub_f32_e32 v62, v54, v3
	v_sub_f32_e32 v63, v55, v3
	v_sub_f32_e32 v68, v48, v3
	v_sub_f32_e32 v73, v49, v3
	v_sub_f32_e32 v74, v50, v3
	v_sub_f32_e32 v75, v51, v3
	v_sub_f32_e32 v80, v44, v3
	v_sub_f32_e32 v81, v45, v3
	v_sub_f32_e32 v82, v46, v3
	v_sub_f32_e32 v83, v47, v3
	v_exp_f32_e32 v72, v56
	v_exp_f32_e32 v71, v57
	v_exp_f32_e32 v70, v58
	v_exp_f32_e32 v69, v59
	v_exp_f32_e32 v67, v60
	v_exp_f32_e32 v66, v61
	v_exp_f32_e32 v65, v62
	v_exp_f32_e32 v64, v63
	v_exp_f32_e32 v63, v68
	v_exp_f32_e32 v62, v73
	v_exp_f32_e32 v61, v74
	v_exp_f32_e32 v60, v75
	v_exp_f32_e32 v59, v80
	v_exp_f32_e32 v58, v81
	v_exp_f32_e32 v57, v82
	v_exp_f32_e32 v56, v83
	s_and_saveexec_b64 s[0:1], vcc
	s_xor_b64 s[0:1], exec, s[0:1]
	s_cbranch_execz .LBB0_438
	v_add_f32_e32 v44, 0, v72
	v_add_f32_e32 v44, v71, v44
	v_add_f32_e32 v44, v70, v44
	v_add_f32_e32 v44, v69, v44
	v_add_f32_e32 v44, v67, v44
	v_add_f32_e32 v44, v66, v44
	v_add_f32_e32 v44, v65, v44
	v_add_f32_e32 v44, v64, v44
	v_add_f32_e32 v44, v63, v44
	v_add_f32_e32 v44, v62, v44
	v_add_f32_e32 v44, v61, v44
	v_add_f32_e32 v44, v60, v44
	v_add_f32_e32 v44, v59, v44
	v_add_f32_e32 v44, v58, v44
	v_add_f32_e32 v44, v57, v44
	v_add_f32_e32 v68, v56, v44

.LBB0_441:
	s_or_b64 exec, exec, s[14:15]
	ds_bpermute_b32 v3, v223, v1
	s_waitcnt vmcnt(0)
	v_mov_b32_e32 v19, 0
	v_lshlrev_b64 v[202:203], 10, v[110:111]
	v_mov_b32_e32 v18, v19
	s_waitcnt lgkmcnt(0)
	v_max_f32_e32 v3, v1, v3
	ds_bpermute_b32 v12, v224, v3
	v_mov_b32_e32 v17, v19
	v_mov_b32_e32 v16, v19
	v_mov_b32_e32 v23, v19
	v_mov_b32_e32 v22, v19
	s_waitcnt lgkmcnt(0)
	v_max_f32_e32 v3, v3, v12
	v_sub_f32_e32 v1, v1, v3
	v_exp_f32_e32 v12, v1
	v_mov_b32_e32 v21, v19
	v_mov_b32_e32 v20, v19
	v_mov_b32_e32 v27, v19
	v_mul_f32_e32 v1, v2, v12
	ds_bpermute_b32 v1, v223, v1
	v_mov_b32_e32 v26, v19
	v_mov_b32_e32 v25, v19
	v_mov_b32_e32 v24, v19
	v_mov_b32_e32 v15, v19
	s_waitcnt lgkmcnt(0)
	v_fmac_f32_e32 v1, v2, v12
	ds_bpermute_b32 v2, v224, v1
	v_mov_b32_e32 v14, v19
	v_mov_b32_e32 v13, v19
	v_mov_b32_e32 v12, v19
	ds_write2st64_b32 v213, v0, v0 offset1:1
	ds_write2st64_b32 v213, v0, v0 offset0:2 offset1:3
	ds_write2st64_b32 v213, v0, v0 offset0:4 offset1:5
	ds_write2st64_b32 v213, v0, v0 offset0:6 offset1:7
	ds_write2st64_b32 v213, v0, v0 offset0:8 offset1:9
	ds_write2st64_b32 v213, v0, v0 offset0:10 offset1:11
	ds_write2st64_b32 v213, v0, v0 offset0:12 offset1:13
	ds_write2st64_b32 v213, v0, v0 offset0:14 offset1:15
	s_and_saveexec_b64 s[14:15], s[12:13]
	s_cbranch_execz .LBB0_503
	global_load_dwordx4 v[56:59], v[172:173], off
	global_load_dwordx4 v[52:55], v[172:173], off offset:1024
	global_load_dwordx4 v[48:51], v[172:173], off offset:2048
	global_load_dwordx4 v[40:43], v[172:173], off offset:3072
	global_load_dwordx4 v[44:47], v[174:175], off
	global_load_dwordx4 v[36:39], v[176:177], off
	global_load_dwordx4 v[32:35], v[178:179], off
	global_load_dwordx4 v[28:31], v[180:181], off
	s_waitcnt lgkmcnt(8)
	v_add_f32_e32 v1, v1, v2
	v_log_f32_e32 v2, v1
	v_mov_b32_e32 v12, 0
	v_cmp_lt_f32_e32 vcc, 0, v1
	s_mov_b32 s22, 0
	v_add_f32_e32 v2, v3, v2
	v_cndmask_b32_e32 v111, v221, v2, vcc
	s_movk_i32 s12, 0x1000
	s_movk_i32 s23, 0x7f
	s_mov_b64 s[16:17], 0
	v_mov_b32_e32 v116, v218
	v_mov_b32_e32 v13, v12
	v_mov_b32_e32 v14, v12
	v_mov_b32_e32 v15, v12
	v_mov_b32_e32 v24, v12
	v_mov_b32_e32 v25, v12
	v_mov_b32_e32 v26, v12
	v_mov_b32_e32 v27, v12
	v_mov_b32_e32 v20, v12
	v_mov_b32_e32 v21, v12
	v_mov_b32_e32 v22, v12
	v_mov_b32_e32 v23, v12
	v_mov_b32_e32 v16, v12
	v_mov_b32_e32 v17, v12
	v_mov_b32_e32 v18, v12
	v_mov_b32_e32 v19, v12
	s_branch .LBB0_445

.LBB0_503:
	s_or_b64 exec, exec, s[14:15]
	v_mad_i64_i32 v[204:205], s[0:1], v110, 48, v[184:185]
	s_waitcnt lgkmcnt(8)
	v_lshl_add_u64 v[2:3], v[204:205], 2, s[44:45]
	global_load_dword v2, v[2:3], off
	s_waitcnt vmcnt(1)
	ds_read2st64_b32 v[28:29], v213 offset1:1
	ds_read2st64_b32 v[36:37], v213 offset0:6 offset1:7
	v_ashrrev_i32_e32 v229, 4, v226
	v_add_u32_e32 v1, -1, v229
	v_cmp_eq_u32_e32 vcc, v207, v229
	s_or_b64 s[0:1], s[8:9], vcc
	v_cmp_eq_u32_e32 vcc, v207, v1
	s_waitcnt lgkmcnt(1)
	v_and_b32_e32 v3, 0xffffff00, v28
	v_cmp_gt_i32_e64 s[20:21], v207, v229
	s_or_b64 s[18:19], s[0:1], vcc
	v_cmp_eq_u32_e32 vcc, v214, v229
	v_cndmask_b32_e64 v3, v3, 0, s[20:21]
	v_cndmask_b32_e64 v3, v3, v222, s[18:19]
	v_sub_u32_e32 v3, v3, v207
	v_add_u32_e32 v31, 0xff, v3
	v_and_b32_e32 v3, 0xffffff00, v29
	ds_read2st64_b32 v[28:29], v213 offset0:2 offset1:3
	ds_read2st64_b32 v[44:45], v213 offset0:10 offset1:11
	v_cmp_eq_u32_e64 s[0:1], v214, v1
	s_or_b64 s[22:23], vcc, s[0:1]
	v_cmp_eq_u32_e32 vcc, v215, v229
	v_cmp_eq_u32_e64 s[0:1], v215, v1
	s_waitcnt lgkmcnt(1)
	v_and_b32_e32 v28, 0xffffff00, v28
	v_cmp_gt_i32_e64 s[12:13], v215, v229
	s_or_b64 vcc, vcc, s[0:1]
	v_cmp_eq_u32_e64 s[0:1], v216, v229
	v_cndmask_b32_e64 v28, v28, 0, s[12:13]
	v_cndmask_b32_e32 v28, v28, v222, vcc
	v_sub_u32_e32 v28, v28, v215
	v_add_u32_e32 v34, 0xff, v28
	v_cmp_eq_u32_e64 s[14:15], v216, v1
	v_and_b32_e32 v28, 0xffffff00, v29
	v_cmp_gt_i32_e64 s[16:17], v216, v229
	s_or_b64 s[14:15], s[0:1], s[14:15]
	v_cmp_gt_i32_e64 s[24:25], v214, v229
	v_cndmask_b32_e64 v28, v28, 0, s[16:17]
	v_cndmask_b32_e64 v28, v28, v222, s[14:15]
	v_sub_u32_e32 v28, v28, v216
	v_add_u32_e32 v30, 0xff, v28
	ds_read2st64_b32 v[28:29], v213 offset0:4 offset1:5
	v_cndmask_b32_e64 v3, v3, 0, s[24:25]
	v_cndmask_b32_e64 v3, v3, v222, s[22:23]
	v_sub_u32_e32 v3, v3, v214
	s_mov_b32 s72, 0
	s_waitcnt lgkmcnt(0)
	v_and_b32_e32 v28, 0xffffff00, v28
	v_cndmask_b32_e64 v28, v28, 0, s[20:21]
	v_cndmask_b32_e64 v28, v28, v222, s[18:19]
	v_sub_u32_e32 v28, v28, v207
	v_add_u32_e32 v32, 0xff, v28
	v_and_b32_e32 v28, 0xffffff00, v29
	v_and_b32_e32 v29, 0xffffff00, v36
	v_cndmask_b32_e64 v29, v29, 0, s[12:13]
	v_cndmask_b32_e32 v29, v29, v222, vcc
	v_sub_u32_e32 v29, v29, v215
	v_add_u32_e32 v42, 0xff, v29
	v_and_b32_e32 v29, 0xffffff00, v37
	ds_read2st64_b32 v[36:37], v213 offset0:8 offset1:9
	v_cndmask_b32_e64 v29, v29, 0, s[16:17]
	v_cndmask_b32_e64 v29, v29, v222, s[14:15]
	v_sub_u32_e32 v29, v29, v216
	v_add_u32_e32 v41, 0xff, v29
	s_waitcnt lgkmcnt(0)
	v_and_b32_e32 v29, 0xffffff00, v36
	v_cndmask_b32_e64 v29, v29, 0, s[20:21]
	v_cndmask_b32_e64 v29, v29, v222, s[18:19]
	v_sub_u32_e32 v29, v29, v207
	v_add_u32_e32 v39, 0xff, v29
	v_and_b32_e32 v29, 0xffffff00, v37
	v_cndmask_b32_e64 v29, v29, 0, s[24:25]
	v_cndmask_b32_e64 v29, v29, v222, s[22:23]
	v_sub_u32_e32 v29, v29, v214
	v_add_u32_e32 v36, 0xff, v29
	v_and_b32_e32 v29, 0xffffff00, v44
	v_cndmask_b32_e64 v29, v29, 0, s[12:13]
	v_cndmask_b32_e32 v29, v29, v222, vcc
	v_sub_u32_e32 v29, v29, v215
	v_add_u32_e32 v37, 0xff, v29
	v_and_b32_e32 v29, 0xffffff00, v45
	ds_read2st64_b32 v[44:45], v213 offset0:12 offset1:13
	v_cndmask_b32_e64 v29, v29, 0, s[16:17]
	v_cndmask_b32_e64 v29, v29, v222, s[14:15]
	v_sub_u32_e32 v29, v29, v216
	v_add_u32_e32 v33, 0xff, v29
	s_waitcnt lgkmcnt(0)
	v_and_b32_e32 v29, 0xffffff00, v44
	v_cndmask_b32_e64 v29, v29, 0, s[20:21]
	v_cndmask_b32_e64 v29, v29, v222, s[18:19]
	v_sub_u32_e32 v29, v29, v207
	v_add_u32_e32 v35, 0xff, v29
	v_and_b32_e32 v29, 0xffffff00, v45
	ds_read2st64_b32 v[44:45], v213 offset0:14 offset1:15
	v_cndmask_b32_e64 v28, v28, 0, s[24:25]
	v_cndmask_b32_e64 v29, v29, 0, s[24:25]
	v_cndmask_b32_e64 v28, v28, v222, s[22:23]
	v_cndmask_b32_e64 v29, v29, v222, s[22:23]
	s_waitcnt lgkmcnt(0)
	v_and_b32_e32 v38, 0xffffff00, v44
	v_cndmask_b32_e64 v38, v38, 0, s[12:13]
	v_cndmask_b32_e32 v38, v38, v222, vcc
	v_sub_u32_e32 v38, v38, v215
	v_add_u32_e32 v40, 0xff, v38
	v_and_b32_e32 v38, 0xffffff00, v45
	v_cndmask_b32_e64 v38, v38, 0, s[16:17]
	v_cndmask_b32_e64 v38, v38, v222, s[14:15]
	v_sub_u32_e32 v28, v28, v214
	v_sub_u32_e32 v29, v29, v214
	v_sub_u32_e32 v38, v38, v216
	v_add_u32_e32 v3, 0xff, v3
	v_add_u32_e32 v28, 0xff, v28
	v_add_u32_e32 v29, 0xff, v29
	v_add_u32_e32 v38, 0xff, v38
	s_mov_b32 s17, 29
	s_mov_b32 s18, 0
	s_mov_b32 s19, 0
	s_mov_b32 s16, 0

.Lsel_done_1:
	v_mov_b32_e32 v240, s100
	s_nop 1
	v_mov_b32_e32 v1, s94
	v_mov_b32_e32 v239, s98
	v_lshlrev_b32_e32 v2, 12, v1
	s_waitcnt vmcnt(16)
	v_lshlrev_b32_e32 v100, 12, v239
	v_ashrrev_i32_e32 v3, 31, v2
	v_ashrrev_i32_e32 v101, 31, v100
	v_lshl_add_u64 v[4:5], v[200:201], 0, v[2:3]
	v_lshl_add_u64 v[2:3], v[198:199], 0, v[2:3]
	v_lshl_add_u64 v[102:103], v[200:201], 0, v[100:101]
	v_lshl_add_u64 v[100:101], v[198:199], 0, v[100:101]
	global_load_dwordx4 v[128:131], v[4:5], off
	global_load_dwordx4 v[124:127], v[4:5], off offset:1024
	global_load_dwordx4 v[120:123], v[4:5], off offset:2048
	global_load_dwordx4 v[116:119], v[4:5], off offset:3072
	global_load_dwordx4 v[48:51], v[2:3], off
	global_load_dwordx4 v[44:47], v[2:3], off offset:1024
	global_load_dwordx4 v[6:9], v[2:3], off offset:2048
	s_nop 0
	global_load_dwordx4 v[2:5], v[2:3], off offset:3072
	s_nop 0
	global_load_dwordx4 v[144:147], v[102:103], off
	global_load_dwordx4 v[140:143], v[102:103], off offset:1024
	global_load_dwordx4 v[136:139], v[102:103], off offset:2048
	global_load_dwordx4 v[132:135], v[102:103], off offset:3072
	global_load_dwordx4 v[112:115], v[100:101], off
	global_load_dwordx4 v[108:111], v[100:101], off offset:1024
	global_load_dwordx4 v[104:107], v[100:101], off offset:2048
	s_nop 0
	global_load_dwordx4 v[100:103], v[100:101], off offset:3072
	v_cmp_lt_i32_e64 s[0:1], -1, v236
	s_and_saveexec_b64 s[12:13], s[0:1]
	s_xor_b64 s[20:21], exec, s[12:13]
	s_cbranch_execz .LBB0_586
	v_lshlrev_b32_e32 v236, 1, v236
	v_cmp_ne_u32_e64 s[12:13], v208, v236
	v_cmp_ge_i32_e64 s[14:15], v234, v229
	v_cmp_eq_u32_e64 s[0:1], v208, v236
	s_or_b64 s[12:13], s[12:13], s[14:15]
	s_mov_b64 s[14:15], -1
	s_and_saveexec_b64 s[22:23], s[12:13]
	v_or_b32_e32 v234, 1, v236
	v_cmp_eq_u32_e64 s[12:13], v208, v234
	v_cmp_lt_i32_e64 s[14:15], v235, v229
	s_and_b64 s[12:13], s[12:13], s[14:15]
	s_orn2_b64 s[14:15], s[12:13], exec
	s_or_b64 exec, exec, s[22:23]
	v_cndmask_b32_e64 v243, 0, v151, s[0:1]
	v_cndmask_b32_e64 v242, 0, v150, s[0:1]
	v_cndmask_b32_e64 v245, 0, v11, s[0:1]
	v_cndmask_b32_e64 v244, 0, v10, s[0:1]
	s_waitcnt vmcnt(16)
	v_mfma_f32_16x16x32_fp8_fp8 v[234:237], v[80:81], v[242:243], 0
	s_and_b64 s[12:13], s[0:1], s[14:15]
	v_mfma_f32_16x16x32_fp8_fp8 v[80:83], v[82:83], v[244:245], v[234:237]
	s_nop 5
	v_cndmask_b32_e64 v235, v151, 0, s[0:1]
	v_cndmask_b32_e64 v234, v150, 0, s[0:1]
	v_cndmask_b32_e64 v237, v11, 0, s[0:1]
	v_cndmask_b32_e64 v236, v10, 0, s[0:1]
	v_mfma_f32_16x16x32_fp8_fp8 v[80:83], v[96:97], v[234:235], v[80:83]
	s_xor_b64 s[0:1], s[0:1], -1
	s_and_b64 s[0:1], s[14:15], s[0:1]
	v_mfma_f32_16x16x32_fp8_fp8 v[80:83], v[98:99], v[236:237], v[80:83]
	v_mfma_f32_16x16x32_fp8_fp8 v[96:99], v[76:77], v[242:243], 0
	v_mfma_f32_16x16x32_fp8_fp8 v[76:79], v[78:79], v[244:245], v[96:99]
	s_nop 5
	v_mfma_f32_16x16x32_fp8_fp8 v[76:79], v[92:93], v[234:235], v[76:79]
	v_mfma_f32_16x16x32_fp8_fp8 v[76:79], v[94:95], v[236:237], v[76:79]
	v_mfma_f32_16x16x32_fp8_fp8 v[92:95], v[72:73], v[242:243], 0
	v_mfma_f32_16x16x32_fp8_fp8 v[72:75], v[74:75], v[244:245], v[92:95]
	s_nop 5
	v_mfma_f32_16x16x32_fp8_fp8 v[72:75], v[88:89], v[234:235], v[72:75]
	v_mfma_f32_16x16x32_fp8_fp8 v[72:75], v[90:91], v[236:237], v[72:75]
	v_mfma_f32_16x16x32_fp8_fp8 v[88:91], v[68:69], v[242:243], 0
	v_mfma_f32_16x16x32_fp8_fp8 v[68:71], v[70:71], v[244:245], v[88:91]
	s_nop 5
	v_mfma_f32_16x16x32_fp8_fp8 v[68:71], v[84:85], v[234:235], v[68:71]
	v_max_f32_e32 v84, v80, v81
	v_max_f32_e32 v85, v82, v83
	v_mfma_f32_16x16x32_fp8_fp8 v[68:71], v[86:87], v[236:237], v[68:71]
	v_max_f32_e32 v86, v78, v79
	v_max3_f32 v86, v76, v77, v86
	v_max3_f32 v84, v84, v85, v86
	v_max_f32_e32 v85, v74, v75
	v_max3_f32 v85, v72, v73, v85
	s_nop 2
	v_max_f32_e32 v86, v70, v71
	v_max3_f32 v86, v68, v69, v86
	v_max3_f32 v84, v84, v85, v86
	v_mov_b32_e32 v85, v84
	s_nop 1
	v_permlane16_swap_b32_e32 v84, v85
	v_max_f32_e32 v84, v84, v85
	v_mov_b32_e32 v85, v84
	s_nop 1
	v_permlane32_swap_b32_e32 v84, v85
	v_max_f32_e32 v84, v84, v85
	v_mul_f32_e64 v84, v84, s76
	v_max_f32_e32 v84, v238, v84
	v_cndmask_b32_e64 v85, v238, v84, s[14:15]
	v_sub_f32_e32 v88, 0x41000000, v85
	v_fma_f32 v80, v80, s76, v88
	v_fma_f32 v81, v81, s76, v88
	v_fma_f32 v76, v76, s76, v88
	v_fma_f32 v77, v77, s76, v88
	v_exp_f32_e32 v80, v80
	v_exp_f32_e32 v81, v81
	v_exp_f32_e32 v76, v76
	v_exp_f32_e32 v77, v77
	v_fma_f32 v82, v82, s76, v88
	v_fma_f32 v83, v83, s76, v88
	v_fma_f32 v78, v78, s76, v88
	v_fma_f32 v79, v79, s76, v88
	v_exp_f32_e32 v82, v82
	v_exp_f32_e32 v83, v83
	v_exp_f32_e32 v78, v78
	v_exp_f32_e32 v79, v79
	v_cvt_pk_fp8_f32 v90, v76, v77
	v_cvt_pk_fp8_f32 v89, v80, v81
	v_sub_f32_e32 v84, v238, v85
	v_exp_f32_e32 v84, v84
	v_cvt_pk_fp8_f32 v90, v78, v79 op_sel:[0,0,1]
	v_cvt_pk_fp8_f32 v89, v82, v83 op_sel:[0,0,1]
	v_fma_f32 v72, v72, s76, v88
	v_pk_mul_f32 v[42:43], v[42:43], v[84:85] op_sel_hi:[1,0]
	v_pk_mul_f32 v[40:41], v[40:41], v[84:85] op_sel_hi:[1,0]
	v_cndmask_b32_e64 v87, 0, v90, s[12:13]
	v_cndmask_b32_e64 v86, 0, v89, s[12:13]
	v_pk_mul_f32 v[38:39], v[38:39], v[84:85] op_sel_hi:[1,0]
	v_pk_mul_f32 v[36:37], v[36:37], v[84:85] op_sel_hi:[1,0]
	v_pk_mul_f32 v[34:35], v[34:35], v[84:85] op_sel_hi:[1,0]
	v_pk_mul_f32 v[32:33], v[32:33], v[84:85] op_sel_hi:[1,0]
	v_fma_f32 v73, v73, s76, v88
	v_mfma_f32_16x16x32_fp8_fp8 v[40:43], v[24:25], v[86:87], v[40:43]
	v_fma_f32 v24, v68, s76, v88
	v_exp_f32_e32 v72, v72
	v_exp_f32_e32 v73, v73
	v_mfma_f32_16x16x32_fp8_fp8 v[36:39], v[20:21], v[86:87], v[36:39]
	v_exp_f32_e32 v68, v24
	v_pk_mul_f32 v[30:31], v[30:31], v[84:85] op_sel_hi:[1,0]
	v_pk_mul_f32 v[28:29], v[28:29], v[84:85] op_sel_hi:[1,0]
	v_mfma_f32_16x16x32_fp8_fp8 v[32:35], v[16:17], v[86:87], v[32:35]
	v_fma_f32 v16, v69, s76, v88
	v_exp_f32_e32 v69, v16
	v_fma_f32 v16, v70, s76, v88
	v_mfma_f32_16x16x32_fp8_fp8 v[28:31], v[12:13], v[86:87], v[28:31]
	v_cndmask_b32_e64 v13, 0, v90, s[0:1]
	v_cndmask_b32_e64 v12, 0, v89, s[0:1]
	v_fma_f32 v74, v74, s76, v88
	v_fma_f32 v75, v75, s76, v88
	v_mfma_f32_16x16x32_fp8_fp8 v[36:39], v[60:61], v[12:13], v[36:39]
	v_exp_f32_e32 v60, v16
	v_fma_f32 v16, v71, s76, v88
	v_exp_f32_e32 v74, v74
	v_mfma_f32_16x16x32_fp8_fp8 v[32:35], v[56:57], v[12:13], v[32:35]
	v_exp_f32_e32 v75, v75
	v_exp_f32_e32 v61, v16
	v_cvt_pk_fp8_f32 v57, v68, v69
	v_cvt_pk_fp8_f32 v56, v72, v73
	v_mfma_f32_16x16x32_fp8_fp8 v[40:43], v[64:65], v[12:13], v[40:43]
	v_mov_b32_e32 v238, v85
	v_cvt_pk_fp8_f32 v57, v60, v61 op_sel:[0,0,1]
	v_cvt_pk_fp8_f32 v56, v74, v75 op_sel:[0,0,1]
	v_mfma_f32_16x16x32_fp8_fp8 v[28:31], v[52:53], v[12:13], v[28:31]
	v_cndmask_b32_e64 v13, 0, v57, s[12:13]
	v_cndmask_b32_e64 v12, 0, v56, s[12:13]
	s_nop 1
	v_mfma_f32_16x16x32_fp8_fp8 v[24:27], v[26:27], v[12:13], v[40:43]
	v_mfma_f32_16x16x32_fp8_fp8 v[20:23], v[22:23], v[12:13], v[36:39]
	s_nop 2
	v_mfma_f32_16x16x32_fp8_fp8 v[16:19], v[18:19], v[12:13], v[32:35]
	s_nop 2
	v_pk_add_f32 v[34:35], v[76:77], v[80:81]
	v_pk_add_f32 v[32:33], v[78:79], v[82:83]
	v_mfma_f32_16x16x32_fp8_fp8 v[12:15], v[14:15], v[12:13], v[28:31]
	s_nop 2
	v_cndmask_b32_e64 v31, 0, v57, s[0:1]
	v_cndmask_b32_e64 v30, 0, v56, s[0:1]
	v_pk_add_f32 v[28:29], v[72:73], v[34:35]
	s_nop 0
	v_mfma_f32_16x16x32_fp8_fp8 v[40:43], v[66:67], v[30:31], v[24:27]
	s_nop 2
	v_add_f32_e64 v24, v74, v32
	v_add_f32_e64 v25, v75, v33
	v_pk_add_f32 v[26:27], v[68:69], v[28:29]
	v_pk_add_f32 v[24:25], v[60:61], v[24:25]
	v_mfma_f32_16x16x32_fp8_fp8 v[36:39], v[62:63], v[30:31], v[20:23]
	v_mfma_f32_16x16x32_fp8_fp8 v[32:35], v[58:59], v[30:31], v[16:19]
	s_nop 1
	v_pk_mov_b32 v[20:21], v[26:27], v[24:25] op_sel:[1,0]
	v_mov_b32_e32 v27, v25
	v_pk_add_f32 v[20:21], v[20:21], v[26:27]
	v_mfma_f32_16x16x32_fp8_fp8 v[28:31], v[54:55], v[30:31], v[12:15]
	v_add_f32_e32 v16, v20, v21
	v_cndmask_b32_e64 v237, 0, v16, s[14:15]
	v_fmac_f32_e32 v237, v241, v84
.LBB0_586:
	s_andn2_saveexec_b64 s[12:13], s[20:21]
	s_cbranch_execz .LBB0_592
	v_cmp_ge_i32_e64 s[0:1], v234, v229
	s_and_saveexec_b64 s[14:15], s[0:1]
	s_xor_b64 s[14:15], exec, s[14:15]
	s_cbranch_execz .LBB0_589
	s_waitcnt vmcnt(16)
	v_mfma_f32_16x16x32_fp8_fp8 v[52:55], v[80:81], v[150:151], 0
	v_mfma_f32_16x16x32_fp8_fp8 v[52:55], v[82:83], v[10:11], v[52:55]
	v_mfma_f32_16x16x32_fp8_fp8 v[56:59], v[76:77], v[150:151], 0
	v_mfma_f32_16x16x32_fp8_fp8 v[56:59], v[78:79], v[10:11], v[56:59]
	s_nop 5
	v_mul_f32_e64 v64, v54, s76
	v_mul_f32_e64 v65, v55, s76
	v_pk_mul_f32 v[66:67], v[52:53], s[76:77] op_sel_hi:[1,0]
	v_mfma_f32_16x16x32_fp8_fp8 v[52:55], v[68:69], v[150:151], 0
	v_lshl_or_b32 v68, v234, 6, v212
	v_cmp_le_i32_e64 s[0:1], v68, v228
	v_or_b32_e32 v69, 2, v68
	v_mfma_f32_16x16x32_fp8_fp8 v[60:63], v[72:73], v[150:151], 0
	v_cndmask_b32_e64 v66, v220, v66, s[0:1]
	v_cmp_lt_i32_e64 s[0:1], v68, v228
	v_pk_mul_f32 v[56:57], v[56:57], s[76:77] op_sel_hi:[1,0]
	v_mfma_f32_16x16x32_fp8_fp8 v[60:63], v[74:75], v[10:11], v[60:63]
	v_cndmask_b32_e64 v67, v220, v67, s[0:1]
	v_cmp_le_i32_e64 s[0:1], v69, v228
	v_or_b32_e32 v69, 3, v68
	v_pk_mul_f32 v[58:59], v[58:59], s[76:77] op_sel_hi:[1,0]
	v_cndmask_b32_e64 v64, v220, v64, s[0:1]
	v_cmp_le_i32_e64 s[0:1], v69, v228
	v_or_b32_e32 v69, 16, v68
	v_mfma_f32_16x16x32_fp8_fp8 v[52:55], v[70:71], v[10:11], v[52:55]
	v_cndmask_b32_e64 v65, v220, v65, s[0:1]
	v_cmp_le_i32_e64 s[0:1], v69, v228
	v_pk_mul_f32 v[60:61], v[60:61], s[76:77] op_sel_hi:[1,0]
	v_pk_mul_f32 v[62:63], v[62:63], s[76:77] op_sel_hi:[1,0]
	v_cndmask_b32_e64 v69, v220, v56, s[0:1]
	v_or_b32_e32 v56, 17, v68
	v_cmp_le_i32_e64 s[0:1], v56, v228
	v_or_b32_e32 v56, 18, v68
	v_pk_mul_f32 v[52:53], v[52:53], s[76:77] op_sel_hi:[1,0]
	v_cndmask_b32_e64 v70, v220, v57, s[0:1]
	v_cmp_le_i32_e64 s[0:1], v56, v228
	v_or_b32_e32 v56, 19, v68
	v_pk_mul_f32 v[54:55], v[54:55], s[76:77] op_sel_hi:[1,0]
	v_cndmask_b32_e64 v71, v220, v58, s[0:1]
	v_cmp_le_i32_e64 s[0:1], v56, v228
	v_or_b32_e32 v56, 32, v68
	s_nop 0
	v_cndmask_b32_e64 v72, v220, v59, s[0:1]
	v_cmp_le_i32_e64 s[0:1], v56, v228
	v_or_b32_e32 v56, 33, v68
	s_nop 0
	v_cndmask_b32_e64 v73, v220, v60, s[0:1]
	v_cmp_le_i32_e64 s[0:1], v56, v228
	v_or_b32_e32 v56, 34, v68
	s_nop 0
	v_cndmask_b32_e64 v74, v220, v61, s[0:1]
	v_cmp_le_i32_e64 s[0:1], v56, v228
	v_or_b32_e32 v56, 35, v68
	s_nop 0
	v_cndmask_b32_e64 v75, v220, v62, s[0:1]
	v_cmp_le_i32_e64 s[0:1], v56, v228
	v_or_b32_e32 v56, 48, v68
	s_nop 0
	v_cndmask_b32_e64 v76, v220, v63, s[0:1]
	v_cmp_le_i32_e64 s[0:1], v56, v228
	s_nop 1
	v_cndmask_b32_e64 v77, v220, v52, s[0:1]
	v_or_b32_e32 v52, 49, v68
	v_cmp_le_i32_e64 s[0:1], v52, v228
	v_or_b32_e32 v52, 50, v68
	s_nop 0
	v_cndmask_b32_e64 v78, v220, v53, s[0:1]
	v_cmp_le_i32_e64 s[0:1], v52, v228
	v_or_b32_e32 v52, 51, v68
	v_max_f32_e32 v53, v64, v65
	v_cndmask_b32_e64 v79, v220, v54, s[0:1]
	v_cmp_le_i32_e64 s[0:1], v52, v228
	v_max_f32_e32 v54, v71, v72
	v_max_f32_e32 v52, v66, v67
	v_cndmask_b32_e64 v80, v220, v55, s[0:1]
	v_max3_f32 v54, v69, v70, v54
	v_max3_f32 v52, v52, v53, v54
	v_max_f32_e32 v53, v75, v76
	v_max_f32_e32 v54, v79, v80
	v_max3_f32 v53, v73, v74, v53
	v_max3_f32 v54, v77, v78, v54
	v_max3_f32 v52, v52, v53, v54
	v_mov_b32_e32 v53, v52
	v_cmp_lt_f32_e64 s[0:1], s83, v66
	s_nop 1
	v_permlane16_swap_b32_e32 v52, v53
	v_max_f32_e32 v52, v52, v53
	v_mov_b32_e32 v53, v52
	s_nop 1
	v_permlane32_swap_b32_e32 v52, v53
	v_max3_f32 v81, v238, v52, v53
	v_sub_f32_e32 v82, 0x41000000, v81
	v_add_f32_e32 v52, v66, v82
	v_exp_f32_e32 v52, v52
	v_add_f32_e32 v53, v67, v82
	v_exp_f32_e32 v53, v53
	v_add_f32_e32 v54, v64, v82
	v_exp_f32_e32 v54, v54
	v_add_f32_e32 v55, v65, v82
	v_exp_f32_e32 v55, v55
	v_add_f32_e32 v56, v69, v82
	v_cndmask_b32_e64 v52, 0, v52, s[0:1]
	v_cmp_lt_f32_e64 s[0:1], s83, v67
	v_exp_f32_e32 v58, v56
	v_add_f32_e32 v59, v70, v82
	v_cndmask_b32_e64 v53, 0, v53, s[0:1]
	v_cmp_lt_f32_e64 s[0:1], s83, v64
	v_exp_f32_e32 v59, v59
	v_add_f32_e32 v60, v71, v82
	v_cndmask_b32_e64 v54, 0, v54, s[0:1]
	v_cmp_lt_f32_e64 s[0:1], s83, v65
	v_exp_f32_e32 v60, v60
	v_add_f32_e32 v61, v72, v82
	v_cndmask_b32_e64 v55, 0, v55, s[0:1]
	v_cmp_lt_f32_e64 s[0:1], s83, v69
	v_exp_f32_e32 v61, v61
	v_add_f32_e32 v62, v73, v82
	v_cndmask_b32_e64 v58, 0, v58, s[0:1]
	v_cmp_lt_f32_e64 s[0:1], s83, v70
	v_exp_f32_e32 v62, v62
	v_add_f32_e32 v63, v74, v82
	v_cndmask_b32_e64 v59, 0, v59, s[0:1]
	v_cmp_lt_f32_e64 s[0:1], s83, v71
	v_mov_b32_e32 v70, 0
	v_mov_b32_e32 v71, 0
	v_exp_f32_e32 v63, v63
	v_add_f32_e32 v64, v75, v82
	v_cvt_pk_fp8_f32 v70, v52, v53
	v_cvt_pk_fp8_f32 v71, v58, v59
	v_cndmask_b32_e64 v60, 0, v60, s[0:1]
	v_cmp_lt_f32_e64 s[0:1], s83, v72
	v_exp_f32_e32 v64, v64
	v_add_f32_e32 v65, v76, v82
	v_sub_f32_e32 v83, v238, v81
	v_pk_add_f32 v[56:57], v[52:53], 0 op_sel_hi:[1,0]
	v_cndmask_b32_e64 v61, 0, v61, s[0:1]
	v_cmp_lt_f32_e64 s[0:1], s83, v73
	v_exp_f32_e32 v65, v65
	v_add_f32_e32 v66, v77, v82
	v_add_f32_e32 v53, v80, v82
	v_cndmask_b32_e64 v62, 0, v62, s[0:1]
	v_cmp_lt_f32_e64 s[0:1], s83, v74
	v_exp_f32_e32 v66, v66
	v_add_f32_e32 v67, v78, v82
	v_exp_f32_e32 v52, v83
	v_exp_f32_e32 v53, v53
	v_cndmask_b32_e64 v63, 0, v63, s[0:1]
	v_cmp_lt_f32_e64 s[0:1], s83, v75
	v_exp_f32_e32 v67, v67
	v_cvt_pk_fp8_f32 v70, v54, v55 op_sel:[0,0,1]
	v_cvt_pk_fp8_f32 v71, v60, v61 op_sel:[0,0,1]
	v_cndmask_b32_e64 v64, 0, v64, s[0:1]
	v_cmp_lt_f32_e64 s[0:1], s83, v76
	v_add_f32_e32 v68, v79, v82
	v_exp_f32_e32 v68, v68
	v_cndmask_b32_e64 v65, 0, v65, s[0:1]
	v_cmp_lt_f32_e64 s[0:1], s83, v77
	v_pk_mul_f32 v[34:35], v[34:35], v[52:53] op_sel_hi:[1,0]
	v_pk_mul_f32 v[32:33], v[32:33], v[52:53] op_sel_hi:[1,0]
	v_cndmask_b32_e64 v66, 0, v66, s[0:1]
	v_cmp_lt_f32_e64 s[0:1], s83, v78
	v_mfma_f32_16x16x32_fp8_fp8 v[32:35], v[16:17], v[70:71], v[32:35]
	v_mov_b32_e32 v16, 0
	v_cndmask_b32_e64 v67, 0, v67, s[0:1]
	v_mov_b32_e32 v17, 0
	v_cvt_pk_fp8_f32 v16, v62, v63
	v_cvt_pk_fp8_f32 v17, v66, v67
	v_cmp_lt_f32_e64 s[0:1], s83, v79
	v_pk_mul_f32 v[38:39], v[38:39], v[52:53] op_sel_hi:[1,0]
	v_pk_mul_f32 v[36:37], v[36:37], v[52:53] op_sel_hi:[1,0]
	v_cndmask_b32_e64 v68, 0, v68, s[0:1]
	v_cmp_lt_f32_e64 s[0:1], s83, v80
	v_pk_mul_f32 v[30:31], v[30:31], v[52:53] op_sel_hi:[1,0]
	v_pk_mul_f32 v[28:29], v[28:29], v[52:53] op_sel_hi:[1,0]
	v_cndmask_b32_e64 v69, 0, v53, s[0:1]
	v_mfma_f32_16x16x32_fp8_fp8 v[36:39], v[20:21], v[70:71], v[36:39]
	v_cvt_pk_fp8_f32 v16, v64, v65 op_sel:[0,0,1]
	v_cvt_pk_fp8_f32 v17, v68, v69 op_sel:[0,0,1]
	v_pk_add_f32 v[20:21], v[58:59], v[56:57]
	v_mfma_f32_16x16x32_fp8_fp8 v[28:31], v[12:13], v[70:71], v[28:31]
	v_add_f32_e64 v12, v54, 0
	v_add_f32_e64 v13, v55, 0
	v_pk_mul_f32 v[42:43], v[42:43], v[52:53] op_sel_hi:[1,0]
	v_pk_add_f32 v[12:13], v[60:61], v[12:13]
	v_pk_mul_f32 v[40:41], v[40:41], v[52:53] op_sel_hi:[1,0]
	v_pk_add_f32 v[20:21], v[62:63], v[20:21]
	v_pk_add_f32 v[12:13], v[64:65], v[12:13]
	v_mfma_f32_16x16x32_fp8_fp8 v[40:43], v[24:25], v[70:71], v[40:43]
	v_add_f32_e64 v12, v68, v12
	v_add_f32_e64 v13, v69, v13
	v_pk_add_f32 v[20:21], v[66:67], v[20:21]
	v_mov_b32_e32 v238, v81
	v_mfma_f32_16x16x32_fp8_fp8 v[36:39], v[22:23], v[16:17], v[36:39]
	v_pk_mov_b32 v[22:23], v[20:21], v[12:13] op_sel:[1,0]
	v_mov_b32_e32 v21, v13
	v_pk_add_f32 v[12:13], v[22:23], v[20:21]
	v_mfma_f32_16x16x32_fp8_fp8 v[40:43], v[26:27], v[16:17], v[40:43]
	v_add_f32_e32 v237, v12, v13
	v_fmac_f32_e32 v237, v241, v52
	v_mfma_f32_16x16x32_fp8_fp8 v[32:35], v[18:19], v[16:17], v[32:35]
	v_mfma_f32_16x16x32_fp8_fp8 v[28:31], v[14:15], v[16:17], v[28:31]
.LBB0_589:
	s_andn2_saveexec_b64 s[0:1], s[14:15]
	s_cbranch_execz .LBB0_591
	s_waitcnt vmcnt(16)
	v_mfma_f32_16x16x32_fp8_fp8 v[52:55], v[80:81], v[150:151], 0
	v_mfma_f32_16x16x32_fp8_fp8 v[52:55], v[82:83], v[10:11], v[52:55]
	v_mfma_f32_16x16x32_fp8_fp8 v[56:59], v[76:77], v[150:151], 0
	v_mfma_f32_16x16x32_fp8_fp8 v[60:63], v[72:73], v[150:151], 0
	s_nop 5
	v_mul_f32_e64 v64, v54, s76
	v_mul_f32_e64 v65, v55, s76
	v_pk_mul_f32 v[66:67], v[52:53], s[76:77] op_sel_hi:[1,0]
	v_mfma_f32_16x16x32_fp8_fp8 v[52:55], v[68:69], v[150:151], 0
	v_max_f32_e32 v68, v66, v67
	v_max_f32_e32 v69, v64, v65
	v_mfma_f32_16x16x32_fp8_fp8 v[56:59], v[78:79], v[10:11], v[56:59]
	v_mfma_f32_16x16x32_fp8_fp8 v[60:63], v[74:75], v[10:11], v[60:63]
	v_mfma_f32_16x16x32_fp8_fp8 v[52:55], v[70:71], v[10:11], v[52:55]
	s_nop 5
	v_mul_f32_e64 v58, v58, s76
	v_mul_f32_e64 v59, v59, s76
	v_pk_mul_f32 v[56:57], v[56:57], s[76:77] op_sel_hi:[1,0]
	v_max_f32_e32 v70, v58, v59
	v_pk_mul_f32 v[62:63], v[62:63], s[76:77] op_sel_hi:[1,0]
	v_max3_f32 v70, v56, v57, v70
	v_pk_mul_f32 v[54:55], v[54:55], s[76:77] op_sel_hi:[1,0]
	v_pk_mul_f32 v[60:61], v[60:61], s[76:77] op_sel_hi:[1,0]
	v_pk_mul_f32 v[52:53], v[52:53], s[76:77] op_sel_hi:[1,0]
	v_max3_f32 v68, v68, v69, v70
	v_max_f32_e32 v69, v62, v63
	v_max_f32_e32 v70, v54, v55
	v_max3_f32 v69, v60, v61, v69
	v_max3_f32 v70, v52, v53, v70
	v_max3_f32 v68, v68, v69, v70
	v_mov_b32_e32 v69, v68
	v_mov_b32_e32 v70, 0
	v_mov_b32_e32 v71, 0
	s_nop 1
	v_permlane16_swap_b32_e32 v68, v69
	v_max_f32_e32 v68, v68, v69
	v_mov_b32_e32 v69, v68
	s_nop 1
	v_permlane32_swap_b32_e32 v68, v69
	v_max3_f32 v72, v238, v68, v69
	v_sub_f32_e32 v74, 0x41000000, v72
	v_add_f32_e32 v66, v66, v74
	v_add_f32_e32 v67, v67, v74
	v_add_f32_e32 v56, v56, v74
	v_add_f32_e32 v57, v57, v74
	v_exp_f32_e32 v66, v66
	v_exp_f32_e32 v67, v67
	v_exp_f32_e32 v56, v56
	v_exp_f32_e32 v57, v57
	v_add_f32_e32 v64, v64, v74
	v_add_f32_e32 v65, v65, v74
	v_add_f32_e32 v58, v58, v74
	v_add_f32_e32 v59, v59, v74
	v_exp_f32_e32 v64, v64
	v_exp_f32_e32 v65, v65
	v_exp_f32_e32 v58, v58
	v_exp_f32_e32 v59, v59
	v_cvt_pk_fp8_f32 v70, v66, v67
	v_cvt_pk_fp8_f32 v71, v56, v57
	v_sub_f32_e32 v73, v238, v72
	v_pk_add_f32 v[68:69], v[66:67], 0 op_sel_hi:[1,0]
	v_exp_f32_e32 v66, v73
	v_add_f32_e32 v60, v60, v74
	v_add_f32_e32 v61, v61, v74
	v_add_f32_e32 v52, v52, v74
	v_add_f32_e32 v53, v53, v74
	v_cvt_pk_fp8_f32 v70, v64, v65 op_sel:[0,0,1]
	v_cvt_pk_fp8_f32 v71, v58, v59 op_sel:[0,0,1]
	v_exp_f32_e32 v60, v60
	v_exp_f32_e32 v61, v61
	v_exp_f32_e32 v52, v52
	v_exp_f32_e32 v53, v53
	v_pk_mul_f32 v[34:35], v[34:35], v[66:67] op_sel_hi:[1,0]
	v_pk_mul_f32 v[32:33], v[32:33], v[66:67] op_sel_hi:[1,0]
	v_add_f32_e32 v62, v62, v74
	v_add_f32_e32 v63, v63, v74
	v_add_f32_e32 v54, v54, v74
	v_add_f32_e32 v55, v55, v74
	v_mfma_f32_16x16x32_fp8_fp8 v[32:35], v[16:17], v[70:71], v[32:35]
	v_mov_b32_e32 v16, 0
	v_mov_b32_e32 v17, 0
	v_exp_f32_e32 v62, v62
	v_exp_f32_e32 v63, v63
	v_exp_f32_e32 v54, v54
	v_exp_f32_e32 v55, v55
	v_cvt_pk_fp8_f32 v16, v60, v61
	v_cvt_pk_fp8_f32 v17, v52, v53
	v_pk_mul_f32 v[42:43], v[42:43], v[66:67] op_sel_hi:[1,0]
	v_pk_mul_f32 v[40:41], v[40:41], v[66:67] op_sel_hi:[1,0]
	v_pk_mul_f32 v[38:39], v[38:39], v[66:67] op_sel_hi:[1,0]
	v_pk_mul_f32 v[36:37], v[36:37], v[66:67] op_sel_hi:[1,0]
	v_pk_mul_f32 v[30:31], v[30:31], v[66:67] op_sel_hi:[1,0]
	v_pk_mul_f32 v[28:29], v[28:29], v[66:67] op_sel_hi:[1,0]
	v_mfma_f32_16x16x32_fp8_fp8 v[40:43], v[24:25], v[70:71], v[40:43]
	v_cvt_pk_fp8_f32 v16, v62, v63 op_sel:[0,0,1]
	v_cvt_pk_fp8_f32 v17, v54, v55 op_sel:[0,0,1]
	v_mov_b32_e32 v238, v72
	v_mfma_f32_16x16x32_fp8_fp8 v[36:39], v[20:21], v[70:71], v[36:39]
	v_add_f32_e64 v20, v56, v68
	v_add_f32_e64 v21, v57, v69
	v_pk_add_f32 v[20:21], v[60:61], v[20:21]
	v_mfma_f32_16x16x32_fp8_fp8 v[28:31], v[12:13], v[70:71], v[28:31]
	v_add_f32_e64 v12, v64, 0
	v_add_f32_e64 v13, v65, 0
	v_pk_add_f32 v[20:21], v[52:53], v[20:21]
	v_pk_add_f32 v[12:13], v[58:59], v[12:13]
	v_mfma_f32_16x16x32_fp8_fp8 v[40:43], v[26:27], v[16:17], v[40:43]
	v_add_f32_e64 v12, v62, v12
	v_add_f32_e64 v13, v63, v13
	v_pk_add_f32 v[12:13], v[54:55], v[12:13]
	v_mfma_f32_16x16x32_fp8_fp8 v[36:39], v[22:23], v[16:17], v[36:39]
	v_pk_mov_b32 v[22:23], v[20:21], v[12:13] op_sel:[1,0]
	v_mov_b32_e32 v21, v13
	v_pk_add_f32 v[12:13], v[22:23], v[20:21]
	v_mfma_f32_16x16x32_fp8_fp8 v[32:35], v[18:19], v[16:17], v[32:35]
	v_add_f32_e32 v237, v12, v13
	v_fmac_f32_e32 v237, v241, v66
	v_mfma_f32_16x16x32_fp8_fp8 v[28:31], v[14:15], v[16:17], v[28:31]

.Lsel_done_2:
	v_mov_b32_e32 v236, s100
	s_nop 1
	v_mov_b32_e32 v234, s94
	v_mov_b32_e32 v235, s98
	v_lshlrev_b32_e32 v12, 12, v234
	s_waitcnt vmcnt(16)
	v_lshlrev_b32_e32 v52, 12, v235
	v_ashrrev_i32_e32 v13, 31, v12
	v_ashrrev_i32_e32 v53, 31, v52
	v_lshl_add_u64 v[14:15], v[200:201], 0, v[12:13]
	v_lshl_add_u64 v[12:13], v[198:199], 0, v[12:13]
	v_lshl_add_u64 v[54:55], v[200:201], 0, v[52:53]
	v_lshl_add_u64 v[52:53], v[198:199], 0, v[52:53]
	global_load_dwordx4 v[80:83], v[14:15], off
	global_load_dwordx4 v[76:79], v[14:15], off offset:1024
	global_load_dwordx4 v[72:75], v[14:15], off offset:2048
	global_load_dwordx4 v[68:71], v[14:15], off offset:3072
	global_load_dwordx4 v[24:27], v[12:13], off
	global_load_dwordx4 v[20:23], v[12:13], off offset:1024
	global_load_dwordx4 v[16:19], v[12:13], off offset:2048
	s_nop 0
	global_load_dwordx4 v[12:15], v[12:13], off offset:3072
	s_nop 0
	global_load_dwordx4 v[96:99], v[54:55], off
	global_load_dwordx4 v[92:95], v[54:55], off offset:1024
	global_load_dwordx4 v[88:91], v[54:55], off offset:2048
	global_load_dwordx4 v[84:87], v[54:55], off offset:3072
	global_load_dwordx4 v[64:67], v[52:53], off
	global_load_dwordx4 v[60:63], v[52:53], off offset:1024
	global_load_dwordx4 v[56:59], v[52:53], off offset:2048
	s_nop 0
	global_load_dwordx4 v[52:55], v[52:53], off offset:3072
	v_cmp_lt_u32_e64 s[0:1], s24, v231
	s_and_saveexec_b64 s[20:21], s[0:1]
	s_cbranch_execz .LBB0_577
	v_cmp_lt_i32_e64 s[0:1], -1, v240
	s_and_saveexec_b64 s[12:13], s[0:1]
	s_xor_b64 s[22:23], exec, s[12:13]
	s_cbranch_execz .LBB0_601
	v_lshlrev_b32_e32 v240, 1, v240
	v_cmp_ne_u32_e64 s[12:13], v208, v240
	v_cmp_ge_i32_e64 s[14:15], v1, v229
	v_cmp_eq_u32_e64 s[0:1], v208, v240
	s_or_b64 s[12:13], s[12:13], s[14:15]
	s_mov_b64 s[14:15], -1
	s_and_saveexec_b64 s[24:25], s[12:13]
	v_or_b32_e32 v1, 1, v240
	v_cmp_eq_u32_e64 s[12:13], v208, v1
	v_cmp_lt_i32_e64 s[14:15], v239, v229
	s_and_b64 s[12:13], s[12:13], s[14:15]
	s_orn2_b64 s[14:15], s[12:13], exec
	s_or_b64 exec, exec, s[24:25]
	v_cndmask_b32_e64 v245, 0, v151, s[0:1]
	v_cndmask_b32_e64 v244, 0, v150, s[0:1]
	v_cndmask_b32_e64 v247, 0, v11, s[0:1]
	v_cndmask_b32_e64 v246, 0, v10, s[0:1]
	s_waitcnt vmcnt(31)
	v_mfma_f32_16x16x32_fp8_fp8 v[240:243], v[128:129], v[244:245], 0
	s_and_b64 s[12:13], s[0:1], s[14:15]
	v_mfma_f32_16x16x32_fp8_fp8 v[128:131], v[130:131], v[246:247], v[240:243]
	s_nop 5
	v_cndmask_b32_e64 v241, v151, 0, s[0:1]
	v_cndmask_b32_e64 v240, v150, 0, s[0:1]
	v_cndmask_b32_e64 v243, v11, 0, s[0:1]
	v_cndmask_b32_e64 v242, v10, 0, s[0:1]
	s_waitcnt vmcnt(23)
	v_mfma_f32_16x16x32_fp8_fp8 v[128:131], v[144:145], v[240:241], v[128:131]
	s_xor_b64 s[0:1], s[0:1], -1
	s_and_b64 s[0:1], s[14:15], s[0:1]
	v_mfma_f32_16x16x32_fp8_fp8 v[128:131], v[146:147], v[242:243], v[128:131]
	v_mfma_f32_16x16x32_fp8_fp8 v[144:147], v[124:125], v[244:245], 0
	v_mfma_f32_16x16x32_fp8_fp8 v[124:127], v[126:127], v[246:247], v[144:147]
	s_nop 5
	s_waitcnt vmcnt(22)
	v_mfma_f32_16x16x32_fp8_fp8 v[124:127], v[140:141], v[240:241], v[124:127]
	v_max_f32_e32 v1, v128, v129
	v_mfma_f32_16x16x32_fp8_fp8 v[124:127], v[142:143], v[242:243], v[124:127]
	v_mfma_f32_16x16x32_fp8_fp8 v[140:143], v[120:121], v[244:245], 0
	v_mfma_f32_16x16x32_fp8_fp8 v[120:123], v[122:123], v[246:247], v[140:143]
	s_nop 5
	s_waitcnt vmcnt(21)
	v_mfma_f32_16x16x32_fp8_fp8 v[120:123], v[136:137], v[240:241], v[120:123]
	v_mfma_f32_16x16x32_fp8_fp8 v[120:123], v[138:139], v[242:243], v[120:123]
	v_mfma_f32_16x16x32_fp8_fp8 v[136:139], v[116:117], v[244:245], 0
	v_mfma_f32_16x16x32_fp8_fp8 v[116:119], v[118:119], v[246:247], v[136:139]
	s_nop 5
	s_waitcnt vmcnt(20)
	v_mfma_f32_16x16x32_fp8_fp8 v[116:119], v[132:133], v[240:241], v[116:119]
	v_max_f32_e32 v133, v126, v127
	v_max_f32_e32 v132, v130, v131
	v_max3_f32 v133, v124, v125, v133
	v_mfma_f32_16x16x32_fp8_fp8 v[116:119], v[134:135], v[242:243], v[116:119]
	v_max3_f32 v1, v1, v132, v133
	v_max_f32_e32 v132, v122, v123
	v_max3_f32 v132, v120, v121, v132
	s_nop 3
	s_nop 0
	v_max_f32_e32 v133, v118, v119
	v_max3_f32 v133, v116, v117, v133
	v_max3_f32 v1, v1, v132, v133
	v_mov_b32_e32 v132, v1
	s_nop 1
	v_permlane16_swap_b32_e32 v1, v132
	v_max_f32_e32 v1, v1, v132
	v_mov_b32_e32 v132, v1
	s_nop 1
	v_permlane32_swap_b32_e32 v1, v132
	v_max_f32_e32 v1, v1, v132
	v_mul_f32_e64 v1, v1, s76
	v_max_f32_e32 v1, v238, v1
	v_cndmask_b32_e64 v241, v238, v1, s[14:15]
	v_sub_f32_e32 v133, 0x41000000, v241
	v_fma_f32 v128, v128, s76, v133
	v_fma_f32 v129, v129, s76, v133
	v_fma_f32 v124, v124, s76, v133
	v_fma_f32 v125, v125, s76, v133
	v_exp_f32_e32 v128, v128
	v_exp_f32_e32 v129, v129
	v_exp_f32_e32 v124, v124
	v_exp_f32_e32 v125, v125
	v_sub_f32_e32 v1, v238, v241
	v_fma_f32 v130, v130, s76, v133
	v_fma_f32 v131, v131, s76, v133
	v_fma_f32 v126, v126, s76, v133
	v_fma_f32 v127, v127, s76, v133
	v_exp_f32_e32 v132, v1
	v_exp_f32_e32 v130, v130
	v_exp_f32_e32 v131, v131
	v_exp_f32_e32 v126, v126
	v_exp_f32_e32 v127, v127
	v_cvt_pk_fp8_f32 v136, v124, v125
	v_cvt_pk_fp8_f32 v1, v128, v129
	v_pk_mul_f32 v[42:43], v[42:43], v[132:133] op_sel_hi:[1,0]
	v_pk_mul_f32 v[40:41], v[40:41], v[132:133] op_sel_hi:[1,0]
	v_cvt_pk_fp8_f32 v136, v126, v127 op_sel:[0,0,1]
	v_cvt_pk_fp8_f32 v1, v130, v131 op_sel:[0,0,1]
	v_pk_mul_f32 v[34:35], v[34:35], v[132:133] op_sel_hi:[1,0]
	v_pk_mul_f32 v[32:33], v[32:33], v[132:133] op_sel_hi:[1,0]
	v_cndmask_b32_e64 v135, 0, v136, s[12:13]
	v_cndmask_b32_e64 v134, 0, v1, s[12:13]
	v_pk_mul_f32 v[30:31], v[30:31], v[132:133] op_sel_hi:[1,0]
	v_pk_mul_f32 v[28:29], v[28:29], v[132:133] op_sel_hi:[1,0]
	v_fma_f32 v120, v120, s76, v133
	v_fma_f32 v121, v121, s76, v133
	v_mfma_f32_16x16x32_fp8_fp8 v[40:43], v[48:49], v[134:135], v[40:43]
	v_fma_f32 v48, v116, s76, v133
	v_pk_mul_f32 v[38:39], v[38:39], v[132:133] op_sel_hi:[1,0]
	v_pk_mul_f32 v[36:37], v[36:37], v[132:133] op_sel_hi:[1,0]
	v_mfma_f32_16x16x32_fp8_fp8 v[32:35], v[6:7], v[134:135], v[32:35]
	v_exp_f32_e32 v120, v120
	v_exp_f32_e32 v121, v121
	v_fma_f32 v122, v122, s76, v133
	v_mfma_f32_16x16x32_fp8_fp8 v[28:31], v[2:3], v[134:135], v[28:31]
	v_cndmask_b32_e64 v2, 0, v1, s[0:1]
	v_fma_f32 v1, v117, s76, v133
	v_cndmask_b32_e64 v3, 0, v136, s[0:1]
	v_mfma_f32_16x16x32_fp8_fp8 v[36:39], v[44:45], v[134:135], v[36:39]
	v_exp_f32_e32 v44, v48
	v_exp_f32_e32 v45, v1
	v_fma_f32 v1, v118, s76, v133
	v_exp_f32_e32 v48, v1
	v_fma_f32 v1, v119, s76, v133
	v_fma_f32 v123, v123, s76, v133
	v_exp_f32_e32 v49, v1
	s_waitcnt vmcnt(17)
	v_mfma_f32_16x16x32_fp8_fp8 v[32:35], v[104:105], v[2:3], v[32:35]
	v_exp_f32_e32 v122, v122
	v_exp_f32_e32 v123, v123
	v_cvt_pk_fp8_f32 v104, v44, v45
	v_cvt_pk_fp8_f32 v1, v120, v121
	v_mfma_f32_16x16x32_fp8_fp8 v[36:39], v[108:109], v[2:3], v[36:39]
	v_cvt_pk_fp8_f32 v104, v48, v49 op_sel:[0,0,1]
	v_cvt_pk_fp8_f32 v1, v122, v123 op_sel:[0,0,1]
	v_mfma_f32_16x16x32_fp8_fp8 v[40:43], v[112:113], v[2:3], v[40:43]
	s_waitcnt vmcnt(16)
	v_mfma_f32_16x16x32_fp8_fp8 v[28:31], v[100:101], v[2:3], v[28:31]
	v_cndmask_b32_e64 v3, 0, v104, s[12:13]
	v_cndmask_b32_e64 v2, 0, v1, s[12:13]
	s_nop 1
	v_mfma_f32_16x16x32_fp8_fp8 v[36:39], v[46:47], v[2:3], v[36:39]
	v_mfma_f32_16x16x32_fp8_fp8 v[6:9], v[8:9], v[2:3], v[32:35]
	s_nop 2
	v_pk_add_f32 v[34:35], v[124:125], v[128:129]
	v_pk_add_f32 v[32:33], v[126:127], v[130:131]
	v_mfma_f32_16x16x32_fp8_fp8 v[40:43], v[50:51], v[2:3], v[40:43]
	v_add_f32_e64 v32, v122, v32
	v_add_f32_e64 v33, v123, v33
	v_mfma_f32_16x16x32_fp8_fp8 v[2:5], v[4:5], v[2:3], v[28:31]
	v_add_f32_e64 v32, v48, v32
	v_add_f32_e64 v33, v49, v33
	s_nop 0
	v_pk_add_f32 v[28:29], v[120:121], v[34:35]
	v_cndmask_b32_e64 v31, 0, v104, s[0:1]
	v_pk_add_f32 v[28:29], v[44:45], v[28:29]
	v_cndmask_b32_e64 v30, 0, v1, s[0:1]
	v_pk_mov_b32 v[34:35], v[28:29], v[32:33] op_sel:[1,0]
	v_mov_b32_e32 v29, v33
	v_pk_add_f32 v[28:29], v[34:35], v[28:29]
	v_mfma_f32_16x16x32_fp8_fp8 v[40:43], v[114:115], v[30:31], v[40:43]
	v_add_f32_e32 v1, v28, v29
	v_cndmask_b32_e64 v242, 0, v1, s[14:15]
	v_fmac_f32_e32 v242, v237, v132
	v_mfma_f32_16x16x32_fp8_fp8 v[36:39], v[110:111], v[30:31], v[36:39]
	v_mfma_f32_16x16x32_fp8_fp8 v[32:35], v[106:107], v[30:31], v[6:9]
	v_mfma_f32_16x16x32_fp8_fp8 v[28:31], v[102:103], v[30:31], v[2:5]
.LBB0_601:
	s_andn2_saveexec_b64 s[12:13], s[22:23]
	s_cbranch_execz .LBB0_576
	v_cmp_ge_i32_e64 s[0:1], v1, v229
	s_and_saveexec_b64 s[14:15], s[0:1]
	s_xor_b64 s[14:15], exec, s[14:15]
	s_cbranch_execz .LBB0_604
	s_waitcnt vmcnt(16)
	v_mfma_f32_16x16x32_fp8_fp8 v[100:103], v[128:129], v[150:151], 0
	v_lshl_or_b32 v1, v1, 6, v212
	v_cmp_le_i32_e64 s[0:1], v1, v228
	v_mfma_f32_16x16x32_fp8_fp8 v[100:103], v[130:131], v[10:11], v[100:103]
	v_mfma_f32_16x16x32_fp8_fp8 v[104:107], v[124:125], v[150:151], 0
	v_mfma_f32_16x16x32_fp8_fp8 v[104:107], v[126:127], v[10:11], v[104:107]
	s_nop 5
	v_mul_f32_e64 v114, v100, s76
	v_mul_f32_e64 v115, v101, s76
	v_pk_mul_f32 v[112:113], v[102:103], s[76:77] op_sel_hi:[1,0]
	v_cndmask_b32_e64 v114, v220, v114, s[0:1]
	v_mfma_f32_16x16x32_fp8_fp8 v[108:111], v[120:121], v[150:151], 0
	v_cmp_lt_i32_e64 s[0:1], v1, v228
	v_pk_mul_f32 v[104:105], v[104:105], s[76:77] op_sel_hi:[1,0]
	v_pk_mul_f32 v[106:107], v[106:107], s[76:77] op_sel_hi:[1,0]
	v_mfma_f32_16x16x32_fp8_fp8 v[100:103], v[116:117], v[150:151], 0
	v_or_b32_e32 v116, 2, v1
	v_cndmask_b32_e64 v115, v220, v115, s[0:1]
	v_cmp_le_i32_e64 s[0:1], v116, v228
	v_or_b32_e32 v116, 3, v1
	v_mfma_f32_16x16x32_fp8_fp8 v[108:111], v[122:123], v[10:11], v[108:111]
	v_cndmask_b32_e64 v112, v220, v112, s[0:1]
	v_cmp_le_i32_e64 s[0:1], v116, v228
	v_or_b32_e32 v116, 16, v1
	v_mfma_f32_16x16x32_fp8_fp8 v[100:103], v[118:119], v[10:11], v[100:103]
	v_cndmask_b32_e64 v113, v220, v113, s[0:1]
	v_cmp_le_i32_e64 s[0:1], v116, v228
	v_or_b32_e32 v116, 17, v1
	s_nop 0
	v_pk_mul_f32 v[108:109], v[108:109], s[76:77] op_sel_hi:[1,0]
	v_cndmask_b32_e64 v104, v220, v104, s[0:1]
	v_cmp_le_i32_e64 s[0:1], v116, v228
	v_or_b32_e32 v116, 18, v1
	v_pk_mul_f32 v[110:111], v[110:111], s[76:77] op_sel_hi:[1,0]
	v_cndmask_b32_e64 v105, v220, v105, s[0:1]
	v_cmp_le_i32_e64 s[0:1], v116, v228
	v_or_b32_e32 v116, 19, v1
	v_pk_mul_f32 v[100:101], v[100:101], s[76:77] op_sel_hi:[1,0]
	v_cndmask_b32_e64 v106, v220, v106, s[0:1]
	v_cmp_le_i32_e64 s[0:1], v116, v228
	v_or_b32_e32 v116, 32, v1
	v_pk_mul_f32 v[102:103], v[102:103], s[76:77] op_sel_hi:[1,0]
	v_cndmask_b32_e64 v107, v220, v107, s[0:1]
	v_cmp_le_i32_e64 s[0:1], v116, v228
	s_nop 1
	v_cndmask_b32_e64 v116, v220, v108, s[0:1]
	v_or_b32_e32 v108, 33, v1
	v_cmp_le_i32_e64 s[0:1], v108, v228
	v_or_b32_e32 v108, 34, v1
	s_nop 0
	v_cndmask_b32_e64 v117, v220, v109, s[0:1]
	v_cmp_le_i32_e64 s[0:1], v108, v228
	v_or_b32_e32 v108, 35, v1
	s_nop 0
	v_cndmask_b32_e64 v118, v220, v110, s[0:1]
	v_cmp_le_i32_e64 s[0:1], v108, v228
	v_or_b32_e32 v108, 48, v1
	s_nop 0
	v_cndmask_b32_e64 v119, v220, v111, s[0:1]
	v_cmp_le_i32_e64 s[0:1], v108, v228
	s_nop 1
	v_cndmask_b32_e64 v120, v220, v100, s[0:1]
	v_or_b32_e32 v100, 49, v1
	v_cmp_le_i32_e64 s[0:1], v100, v228
	v_or_b32_e32 v100, 50, v1
	v_or_b32_e32 v1, 51, v1
	v_cndmask_b32_e64 v121, v220, v101, s[0:1]
	v_cmp_le_i32_e64 s[0:1], v100, v228
	v_max_f32_e32 v100, v114, v115
	v_max_f32_e32 v101, v112, v113
	v_cndmask_b32_e64 v122, v220, v102, s[0:1]
	v_cmp_le_i32_e64 s[0:1], v1, v228
	v_max_f32_e32 v102, v106, v107
	v_max3_f32 v102, v104, v105, v102
	v_cndmask_b32_e64 v1, v220, v103, s[0:1]
	v_max3_f32 v100, v100, v101, v102
	v_max_f32_e32 v101, v118, v119
	v_max_f32_e32 v102, v122, v1
	v_max3_f32 v101, v116, v117, v101
	v_max3_f32 v102, v120, v121, v102
	v_max3_f32 v100, v100, v101, v102
	v_mov_b32_e32 v101, v100
	v_cmp_lt_f32_e64 s[0:1], s83, v114
	s_nop 1
	v_permlane16_swap_b32_e32 v100, v101
	v_max_f32_e32 v100, v100, v101
	v_mov_b32_e32 v101, v100
	s_nop 1
	v_permlane32_swap_b32_e32 v100, v101
	v_max3_f32 v241, v238, v100, v101
	v_sub_f32_e32 v123, 0x41000000, v241
	v_add_f32_e32 v100, v114, v123
	v_exp_f32_e32 v100, v100
	v_add_f32_e32 v101, v112, v123
	v_exp_f32_e32 v101, v101
	v_add_f32_e32 v102, v104, v123
	v_cndmask_b32_e64 v108, 0, v100, s[0:1]
	v_add_f32_e32 v100, v115, v123
	v_exp_f32_e32 v100, v100
	v_cmp_lt_f32_e64 s[0:1], s83, v115
	v_exp_f32_e32 v110, v102
	v_add_f32_e32 v111, v106, v123
	v_cndmask_b32_e64 v109, 0, v100, s[0:1]
	v_cmp_lt_f32_e64 s[0:1], s83, v112
	v_exp_f32_e32 v111, v111
	v_add_f32_e32 v112, v118, v123
	v_cndmask_b32_e64 v100, 0, v101, s[0:1]
	v_add_f32_e32 v101, v113, v123
	v_exp_f32_e32 v101, v101
	v_cmp_lt_f32_e64 s[0:1], s83, v113
	v_exp_f32_e32 v112, v112
	v_add_f32_e32 v113, v119, v123
	v_cndmask_b32_e64 v101, 0, v101, s[0:1]
	v_cmp_lt_f32_e64 s[0:1], s83, v104
	v_sub_f32_e32 v124, v238, v241
	v_pk_add_f32 v[102:103], v[108:109], 0 op_sel_hi:[1,0]
	v_cndmask_b32_e64 v104, 0, v110, s[0:1]
	v_add_f32_e32 v110, v105, v123
	v_exp_f32_e32 v110, v110
	v_cmp_lt_f32_e64 s[0:1], s83, v105
	v_exp_f32_e32 v113, v113
	v_add_f32_e32 v114, v120, v123
	v_cndmask_b32_e64 v105, 0, v110, s[0:1]
	v_cmp_lt_f32_e64 s[0:1], s83, v106
	v_add_f32_e32 v110, v107, v123
	v_exp_f32_e32 v110, v110
	v_cndmask_b32_e64 v106, 0, v111, s[0:1]
	v_add_f32_e32 v111, v116, v123
	v_exp_f32_e32 v111, v111
	v_cmp_lt_f32_e64 s[0:1], s83, v107
	v_exp_f32_e32 v114, v114
	v_add_f32_e32 v115, v121, v123
	v_cndmask_b32_e64 v107, 0, v110, s[0:1]
	v_cmp_lt_f32_e64 s[0:1], s83, v116
	v_exp_f32_e32 v115, v115
	v_add_f32_e32 v116, v122, v123
	v_cndmask_b32_e64 v110, 0, v111, s[0:1]
	v_add_f32_e32 v111, v117, v123
	v_exp_f32_e32 v111, v111
	v_cmp_lt_f32_e64 s[0:1], s83, v117
	v_exp_f32_e32 v116, v116
	s_nop 0
	v_cndmask_b32_e64 v111, 0, v111, s[0:1]
	v_cmp_lt_f32_e64 s[0:1], s83, v118
	v_mov_b32_e32 v118, 0
	v_cvt_pk_fp8_f32 v118, v108, v109
	v_cndmask_b32_e64 v112, 0, v112, s[0:1]
	v_cmp_lt_f32_e64 s[0:1], s83, v119
	v_mov_b32_e32 v119, 0
	v_cvt_pk_fp8_f32 v119, v104, v105
	v_add_f32_e32 v109, v1, v123
	v_exp_f32_e32 v108, v124
	v_exp_f32_e32 v109, v109
	v_cvt_pk_fp8_f32 v118, v100, v101 op_sel:[0,0,1]
	v_cvt_pk_fp8_f32 v119, v106, v107 op_sel:[0,0,1]
	v_cndmask_b32_e64 v113, 0, v113, s[0:1]
	v_cmp_lt_f32_e64 s[0:1], s83, v120
	v_pk_mul_f32 v[34:35], v[34:35], v[108:109] op_sel_hi:[1,0]
	v_pk_mul_f32 v[32:33], v[32:33], v[108:109] op_sel_hi:[1,0]
	v_cndmask_b32_e64 v114, 0, v114, s[0:1]
	v_cmp_lt_f32_e64 s[0:1], s83, v121
	v_mfma_f32_16x16x32_fp8_fp8 v[32:35], v[6:7], v[118:119], v[32:35]
	v_mov_b32_e32 v6, 0
	v_cndmask_b32_e64 v115, 0, v115, s[0:1]
	v_mov_b32_e32 v7, 0
	v_cvt_pk_fp8_f32 v6, v110, v111
	v_cvt_pk_fp8_f32 v7, v114, v115
	v_cmp_lt_f32_e64 s[0:1], s83, v122
	v_pk_mul_f32 v[38:39], v[38:39], v[108:109] op_sel_hi:[1,0]
	v_pk_mul_f32 v[36:37], v[36:37], v[108:109] op_sel_hi:[1,0]
	v_cndmask_b32_e64 v116, 0, v116, s[0:1]
	v_cmp_lt_f32_e64 s[0:1], s83, v1
	v_pk_mul_f32 v[30:31], v[30:31], v[108:109] op_sel_hi:[1,0]
	v_pk_mul_f32 v[28:29], v[28:29], v[108:109] op_sel_hi:[1,0]
	v_cndmask_b32_e64 v117, 0, v109, s[0:1]
	v_mfma_f32_16x16x32_fp8_fp8 v[36:39], v[44:45], v[118:119], v[36:39]
	v_cvt_pk_fp8_f32 v6, v112, v113 op_sel:[0,0,1]
	v_cvt_pk_fp8_f32 v7, v116, v117 op_sel:[0,0,1]
	v_pk_add_f32 v[44:45], v[104:105], v[102:103]
	v_mfma_f32_16x16x32_fp8_fp8 v[28:31], v[2:3], v[118:119], v[28:31]
	v_add_f32_e64 v2, v100, 0
	v_add_f32_e64 v3, v101, 0
	v_pk_mul_f32 v[42:43], v[42:43], v[108:109] op_sel_hi:[1,0]
	v_pk_add_f32 v[2:3], v[106:107], v[2:3]
	v_pk_mul_f32 v[40:41], v[40:41], v[108:109] op_sel_hi:[1,0]
	v_pk_add_f32 v[44:45], v[110:111], v[44:45]
	v_pk_add_f32 v[2:3], v[112:113], v[2:3]
	v_mfma_f32_16x16x32_fp8_fp8 v[40:43], v[48:49], v[118:119], v[40:43]
	v_add_f32_e64 v2, v116, v2
	v_add_f32_e64 v3, v117, v3
	v_pk_add_f32 v[44:45], v[114:115], v[44:45]
	v_mfma_f32_16x16x32_fp8_fp8 v[36:39], v[46:47], v[6:7], v[36:39]
	v_pk_mov_b32 v[46:47], v[44:45], v[2:3] op_sel:[1,0]
	v_mov_b32_e32 v45, v3
	v_pk_add_f32 v[2:3], v[46:47], v[44:45]
	v_mfma_f32_16x16x32_fp8_fp8 v[40:43], v[50:51], v[6:7], v[40:43]
	v_add_f32_e32 v242, v2, v3
	v_fmac_f32_e32 v242, v237, v108
	v_mfma_f32_16x16x32_fp8_fp8 v[32:35], v[8:9], v[6:7], v[32:35]
	v_mfma_f32_16x16x32_fp8_fp8 v[28:31], v[4:5], v[6:7], v[28:31]
.LBB0_604:
	s_andn2_saveexec_b64 s[0:1], s[14:15]
	s_cbranch_execz .LBB0_575
	s_waitcnt vmcnt(16)
	v_mfma_f32_16x16x32_fp8_fp8 v[100:103], v[128:129], v[150:151], 0
	v_mfma_f32_16x16x32_fp8_fp8 v[100:103], v[130:131], v[10:11], v[100:103]
	v_mfma_f32_16x16x32_fp8_fp8 v[104:107], v[124:125], v[150:151], 0
	v_mfma_f32_16x16x32_fp8_fp8 v[108:111], v[120:121], v[150:151], 0
	s_nop 5
	v_mul_f32_e64 v112, v102, s76
	v_mul_f32_e64 v113, v103, s76
	v_pk_mul_f32 v[114:115], v[100:101], s[76:77] op_sel_hi:[1,0]
	v_mfma_f32_16x16x32_fp8_fp8 v[100:103], v[116:117], v[150:151], 0
	v_max_f32_e32 v1, v114, v115
	v_max_f32_e32 v116, v112, v113
	v_mfma_f32_16x16x32_fp8_fp8 v[104:107], v[126:127], v[10:11], v[104:107]
	v_mfma_f32_16x16x32_fp8_fp8 v[108:111], v[122:123], v[10:11], v[108:111]
	v_mfma_f32_16x16x32_fp8_fp8 v[100:103], v[118:119], v[10:11], v[100:103]
	s_nop 5
	v_mul_f32_e64 v106, v106, s76
	v_mul_f32_e64 v107, v107, s76
	v_pk_mul_f32 v[104:105], v[104:105], s[76:77] op_sel_hi:[1,0]
	v_max_f32_e32 v117, v106, v107
	v_pk_mul_f32 v[110:111], v[110:111], s[76:77] op_sel_hi:[1,0]
	v_max3_f32 v117, v104, v105, v117
	v_pk_mul_f32 v[102:103], v[102:103], s[76:77] op_sel_hi:[1,0]
	v_pk_mul_f32 v[108:109], v[108:109], s[76:77] op_sel_hi:[1,0]
	v_pk_mul_f32 v[100:101], v[100:101], s[76:77] op_sel_hi:[1,0]
	v_max3_f32 v1, v1, v116, v117
	v_max_f32_e32 v116, v110, v111
	v_max_f32_e32 v117, v102, v103
	v_max3_f32 v116, v108, v109, v116
	v_max3_f32 v117, v100, v101, v117
	v_max3_f32 v1, v1, v116, v117
	v_mov_b32_e32 v116, v1
	v_mov_b32_e32 v118, 0
	v_mov_b32_e32 v119, 0
	s_nop 1
	v_permlane16_swap_b32_e32 v1, v116
	v_max_f32_e32 v1, v1, v116
	v_mov_b32_e32 v116, v1
	s_nop 1
	v_permlane32_swap_b32_e32 v1, v116
	v_max3_f32 v241, v238, v1, v116
	v_sub_f32_e32 v120, 0x41000000, v241
	v_add_f32_e32 v114, v114, v120
	v_add_f32_e32 v115, v115, v120
	v_add_f32_e32 v104, v104, v120
	v_add_f32_e32 v105, v105, v120
	v_exp_f32_e32 v114, v114
	v_exp_f32_e32 v115, v115
	v_exp_f32_e32 v104, v104
	v_exp_f32_e32 v105, v105
	v_add_f32_e32 v112, v112, v120
	v_add_f32_e32 v113, v113, v120
	v_add_f32_e32 v106, v106, v120
	v_add_f32_e32 v107, v107, v120
	v_exp_f32_e32 v112, v112
	v_exp_f32_e32 v113, v113
	v_exp_f32_e32 v106, v106
	v_exp_f32_e32 v107, v107
	v_cvt_pk_fp8_f32 v118, v114, v115
	v_cvt_pk_fp8_f32 v119, v104, v105
	v_sub_f32_e32 v1, v238, v241
	v_pk_add_f32 v[116:117], v[114:115], 0 op_sel_hi:[1,0]
	v_exp_f32_e32 v114, v1
	v_add_f32_e32 v108, v108, v120
	v_add_f32_e32 v109, v109, v120
	v_add_f32_e32 v100, v100, v120
	v_add_f32_e32 v101, v101, v120
	v_cvt_pk_fp8_f32 v118, v112, v113 op_sel:[0,0,1]
	v_cvt_pk_fp8_f32 v119, v106, v107 op_sel:[0,0,1]
	v_exp_f32_e32 v108, v108
	v_exp_f32_e32 v109, v109
	v_exp_f32_e32 v100, v100
	v_exp_f32_e32 v101, v101
	v_pk_mul_f32 v[34:35], v[34:35], v[114:115] op_sel_hi:[1,0]
	v_pk_mul_f32 v[32:33], v[32:33], v[114:115] op_sel_hi:[1,0]
	v_add_f32_e32 v110, v110, v120
	v_add_f32_e32 v111, v111, v120
	v_add_f32_e32 v102, v102, v120
	v_add_f32_e32 v1, v103, v120
	v_mfma_f32_16x16x32_fp8_fp8 v[32:35], v[6:7], v[118:119], v[32:35]
	v_mov_b32_e32 v6, 0
	v_mov_b32_e32 v7, 0
	v_exp_f32_e32 v110, v110
	v_exp_f32_e32 v111, v111
	v_exp_f32_e32 v102, v102
	v_exp_f32_e32 v103, v1
	v_cvt_pk_fp8_f32 v6, v108, v109
	v_cvt_pk_fp8_f32 v7, v100, v101
	v_pk_mul_f32 v[42:43], v[42:43], v[114:115] op_sel_hi:[1,0]
	v_pk_mul_f32 v[40:41], v[40:41], v[114:115] op_sel_hi:[1,0]
	v_pk_mul_f32 v[38:39], v[38:39], v[114:115] op_sel_hi:[1,0]
	v_pk_mul_f32 v[36:37], v[36:37], v[114:115] op_sel_hi:[1,0]
	v_pk_mul_f32 v[30:31], v[30:31], v[114:115] op_sel_hi:[1,0]
	v_pk_mul_f32 v[28:29], v[28:29], v[114:115] op_sel_hi:[1,0]
	v_mfma_f32_16x16x32_fp8_fp8 v[40:43], v[48:49], v[118:119], v[40:43]
	v_cvt_pk_fp8_f32 v6, v110, v111 op_sel:[0,0,1]
	v_cvt_pk_fp8_f32 v7, v102, v103 op_sel:[0,0,1]
	v_mfma_f32_16x16x32_fp8_fp8 v[36:39], v[44:45], v[118:119], v[36:39]
	v_add_f32_e64 v44, v104, v116
	v_add_f32_e64 v45, v105, v117
	v_pk_add_f32 v[44:45], v[108:109], v[44:45]
	v_mfma_f32_16x16x32_fp8_fp8 v[28:31], v[2:3], v[118:119], v[28:31]
	v_add_f32_e64 v2, v112, 0
	v_add_f32_e64 v3, v113, 0
	v_pk_add_f32 v[44:45], v[100:101], v[44:45]
	v_pk_add_f32 v[2:3], v[106:107], v[2:3]
	v_mfma_f32_16x16x32_fp8_fp8 v[40:43], v[50:51], v[6:7], v[40:43]
	v_add_f32_e64 v2, v110, v2
	v_add_f32_e64 v3, v111, v3
	v_pk_add_f32 v[2:3], v[102:103], v[2:3]
	v_mfma_f32_16x16x32_fp8_fp8 v[36:39], v[46:47], v[6:7], v[36:39]
	v_pk_mov_b32 v[46:47], v[44:45], v[2:3] op_sel:[1,0]
	v_mov_b32_e32 v45, v3
	v_pk_add_f32 v[2:3], v[46:47], v[44:45]
	v_mfma_f32_16x16x32_fp8_fp8 v[32:35], v[8:9], v[6:7], v[32:35]
	v_add_f32_e32 v242, v2, v3
	v_fmac_f32_e32 v242, v237, v114
	v_mfma_f32_16x16x32_fp8_fp8 v[28:31], v[4:5], v[6:7], v[28:31]
	s_branch .LBB0_575

.Lwin_nodma:
	s_cmp_lt_i32 s12, s22
	s_cbranch_scc1 .Lwin_skip
	s_cmp_gt_i32 s12, s24
	s_cbranch_scc1 .Lwin_skip
	v_add_u32_e32 v61, s36, v60
	ds_read_b128 v[120:123], v61
	ds_read_b128 v[116:119], v61 offset:1024
	ds_read_b128 v[112:115], v61 offset:2048
	ds_read_b128 v[108:111], v61 offset:3072
	ds_read_b128 v[104:107], v61 offset:4096
	ds_read_b128 v[100:103], v61 offset:5120
	ds_read_b128 v[96:99], v61 offset:6144
	ds_read_b128 v[92:95], v61 offset:7168
	ds_read_b128 v[56:59], v61 offset:8192
	ds_read_b128 v[52:55], v61 offset:9216
	ds_read_b128 v[48:51], v61 offset:10240
	ds_read_b128 v[40:43], v61 offset:11264
	ds_read_b128 v[36:39], v61 offset:12288
	ds_read_b128 v[32:35], v61 offset:13312
	ds_read_b128 v[28:31], v61 offset:14336
	ds_read_b128 v[24:27], v61 offset:15360
	s_lshl_b32 s93, s12, 6
	v_mov_b32_e32 v230, s93
	v_add_u32_e32 v230, 0x7f, v230
	s_add_i32 s99, s93, 63
	s_waitcnt lgkmcnt(0)
	s_cmp_ge_i32 s93, s98
	s_cbranch_scc0 .Lwin_msk
	s_cmp_le_i32 s99, s32
	s_cbranch_scc0 .Lwin_msk
	v_mfma_f32_16x16x32_bf16 v[120:123], v[120:123], v[16:19], 0
	v_mfma_f32_16x16x32_bf16 v[112:115], v[112:115], v[16:19], 0
	v_mfma_f32_16x16x32_bf16 v[116:119], v[116:119], v[12:15], v[120:123]
	v_mfma_f32_16x16x32_bf16 v[104:107], v[104:107], v[16:19], 0
	v_mfma_f32_16x16x32_bf16 v[108:111], v[108:111], v[12:15], v[112:115]
	s_nop 5
	v_max_f32_e32 v1, v116, v117
	v_mfma_f32_16x16x32_bf16 v[96:99], v[96:99], v[16:19], 0
	v_max_f32_e32 v2, v118, v119
	v_mfma_f32_16x16x32_bf16 v[100:103], v[100:103], v[12:15], v[104:107]
	v_max_f32_e32 v3, v110, v111
	v_mfma_f32_16x16x32_bf16 v[92:95], v[92:95], v[12:15], v[96:99]
	v_max3_f32 v3, v108, v109, v3
	v_max3_f32 v1, v1, v2, v3
	s_nop 1
	s_nop 1
	v_max_f32_e32 v2, v102, v103
	s_nop 0
	v_max_f32_e32 v3, v94, v95
	v_max3_f32 v2, v100, v101, v2
	v_max3_f32 v3, v92, v93, v3
	v_max3_f32 v1, v1, v2, v3
	v_mov_b32_e32 v2, v1
	s_nop 1
	v_permlane16_swap_b32_e32 v1, v2
	v_max_f32_e32 v1, v1, v2
	v_mov_b32_e32 v2, v1
	s_nop 1
	v_permlane32_swap_b32_e32 v1, v2
	v_max3_f32 v1, v235, v1, v2
	v_sub_f32_e32 v3, v116, v1
	v_exp_f32_e32 v3, v3
	v_sub_f32_e32 v96, v117, v1
	v_exp_f32_e32 v96, v96
	v_sub_f32_e32 v97, v118, v1
	v_exp_f32_e32 v97, v97
	v_sub_f32_e32 v98, v119, v1
	v_exp_f32_e32 v98, v98
	v_sub_f32_e32 v104, v108, v1
	v_add_f32_e32 v99, 0, v3
	v_exp_f32_e32 v104, v104
	v_sub_f32_e32 v105, v109, v1
	v_add_f32_e32 v99, v96, v99
	v_exp_f32_e32 v105, v105
	v_sub_f32_e32 v106, v110, v1
	v_add_f32_e32 v99, v97, v99
	v_exp_f32_e32 v106, v106
	v_sub_f32_e32 v107, v111, v1
	v_add_f32_e32 v99, v98, v99
	v_exp_f32_e32 v107, v107
	v_add_f32_e32 v99, v104, v99
	v_sub_f32_e32 v2, v235, v1
	v_add_f32_e32 v99, v105, v99
	v_sub_f32_e32 v92, v92, v1
	v_add_f32_e32 v99, v106, v99
	v_exp_f32_e32 v109, v92
	v_exp_f32_e32 v92, v2
	v_sub_f32_e32 v2, v93, v1
	v_add_f32_e32 v108, v107, v99
	v_sub_f32_e32 v99, v100, v1
	v_exp_f32_e32 v93, v2
	v_exp_f32_e32 v100, v99
	v_sub_f32_e32 v99, v101, v1
	v_exp_f32_e32 v101, v99
	v_sub_f32_e32 v99, v102, v1
	v_exp_f32_e32 v102, v99
	v_sub_f32_e32 v99, v103, v1
	v_exp_f32_e32 v103, v99
	v_cvt_pk_bf16_f32 v96, v3, v96
	v_cvt_pk_bf16_f32 v97, v97, v98
	v_cvt_pk_bf16_f32 v98, v104, v105
	v_cvt_pk_bf16_f32 v99, v106, v107
	v_pk_mul_f32 v[22:23], v[22:23], v[92:93] op_sel_hi:[1,0]
	v_pk_mul_f32 v[20:21], v[20:21], v[92:93] op_sel_hi:[1,0]
	v_sub_f32_e32 v2, v94, v1
	v_pk_mul_f32 v[46:47], v[46:47], v[92:93] op_sel_hi:[1,0]
	v_pk_mul_f32 v[44:45], v[44:45], v[92:93] op_sel_hi:[1,0]
	v_mfma_f32_16x16x32_bf16 v[20:23], v[52:55], v[96:99], v[20:23]
	v_sub_f32_e32 v52, v95, v1
	v_pk_mul_f32 v[6:7], v[6:7], v[92:93] op_sel_hi:[1,0]
	v_pk_mul_f32 v[4:5], v[4:5], v[92:93] op_sel_hi:[1,0]
	v_mfma_f32_16x16x32_bf16 v[44:47], v[56:59], v[96:99], v[44:47]
	v_exp_f32_e32 v56, v2
	v_pk_mul_f32 v[10:11], v[10:11], v[92:93] op_sel_hi:[1,0]
	v_pk_mul_f32 v[8:9], v[8:9], v[92:93] op_sel_hi:[1,0]
	v_mfma_f32_16x16x32_bf16 v[2:5], v[48:51], v[96:99], v[4:7]
	v_exp_f32_e32 v48, v52
	v_mov_b32_e32 v235, v1
	v_mfma_f32_16x16x32_bf16 v[8:11], v[40:43], v[96:99], v[8:11]
	v_add_f32_e32 v6, v100, v108
	v_add_f32_e32 v6, v101, v6
	v_add_f32_e32 v6, v102, v6
	v_add_f32_e32 v6, v103, v6
	v_cvt_pk_bf16_f32 v40, v100, v101
	v_cvt_pk_bf16_f32 v41, v102, v103
	v_cvt_pk_bf16_f32 v42, v109, v93
	v_cvt_pk_bf16_f32 v43, v56, v48
	v_add_f32_e32 v6, v109, v6
	s_nop 0
	v_mfma_f32_16x16x32_bf16 v[44:47], v[36:39], v[40:43], v[44:47]
	v_mfma_f32_16x16x32_bf16 v[20:23], v[32:35], v[40:43], v[20:23]
	v_add_f32_e32 v32, v93, v6
	v_mfma_f32_16x16x32_bf16 v[4:7], v[28:31], v[40:43], v[2:5]
	v_mfma_f32_16x16x32_bf16 v[8:11], v[24:27], v[40:43], v[8:11]
	s_nop 1
	v_add_f32_e32 v2, v56, v32
	v_add_f32_e32 v234, v48, v2
	v_fmac_f32_e32 v234, v236, v92
	s_branch .Lwin_join
.Lwin_msk:
	v_mfma_f32_16x16x32_bf16 v[120:123], v[120:123], v[16:19], 0
	v_add_u32_e32 v1, v212, v230
	v_add_u32_e32 v2, 0xffffff81, v1
	v_cmp_lt_i32_e32 vcc, v2, v232
	v_mfma_f32_16x16x32_bf16 v[116:119], v[116:119], v[12:15], v[120:123]
	v_cmp_gt_i32_e64 s[0:1], v2, v228
	s_or_b64 vcc, vcc, s[0:1]
	v_cmp_ge_i32_e64 s[0:1], v2, v228
	v_mfma_f32_16x16x32_bf16 v[112:115], v[112:115], v[16:19], 0
	v_mfma_f32_16x16x32_bf16 v[104:107], v[104:107], v[16:19], 0
	s_nop 2
	v_cndmask_b32_e32 v3, v116, v220, vcc
	v_add_u32_e32 v116, 0xffffff82, v1
	v_cmp_lt_i32_e32 vcc, v116, v232
	v_mfma_f32_16x16x32_bf16 v[108:111], v[108:111], v[12:15], v[112:115]
	s_or_b64 vcc, s[0:1], vcc
	v_cndmask_b32_e32 v2, v117, v220, vcc
	s_nop 0
	v_add_u32_e32 v112, 0xffffff83, v1
	v_cmp_lt_i32_e32 vcc, v112, v232
	v_cmp_gt_i32_e64 s[0:1], v112, v228
	s_or_b64 vcc, vcc, s[0:1]
	v_mfma_f32_16x16x32_bf16 v[100:103], v[100:103], v[12:15], v[104:107]
	v_cndmask_b32_e32 v112, v118, v220, vcc
	s_nop 1
	v_add_u32_e32 v104, 0xffffff84, v1
	v_mfma_f32_16x16x32_bf16 v[96:99], v[96:99], v[16:19], 0
	v_cmp_lt_i32_e32 vcc, v104, v232
	v_cmp_gt_i32_e64 s[0:1], v104, v228
	s_or_b64 vcc, vcc, s[0:1]
	v_add_u32_e32 v105, 0xffffff91, v1
	v_cndmask_b32_e32 v104, v119, v220, vcc
	v_cmp_lt_i32_e32 vcc, v105, v232
	v_cmp_gt_i32_e64 s[0:1], v105, v228
	v_mfma_f32_16x16x32_bf16 v[92:95], v[92:95], v[12:15], v[96:99]
	s_or_b64 vcc, vcc, s[0:1]
	v_add_u32_e32 v105, 0xffffffa1, v1
	s_nop 0
	v_add_u32_e32 v97, 0xffffff92, v1
	v_cndmask_b32_e32 v96, v108, v220, vcc
	v_cmp_lt_i32_e32 vcc, v97, v232
	v_cmp_gt_i32_e64 s[0:1], v97, v228
	s_or_b64 vcc, vcc, s[0:1]
	v_add_u32_e32 v98, 0xffffff93, v1
	v_cndmask_b32_e32 v97, v109, v220, vcc
	v_cmp_lt_i32_e32 vcc, v98, v232
	v_cmp_gt_i32_e64 s[0:1], v98, v228
	s_or_b64 vcc, vcc, s[0:1]
	v_add_u32_e32 v99, 0xffffff94, v1
	v_cndmask_b32_e32 v98, v110, v220, vcc
	v_cmp_lt_i32_e32 vcc, v99, v232
	v_cmp_gt_i32_e64 s[0:1], v99, v228
	s_or_b64 vcc, vcc, s[0:1]
	v_cndmask_b32_e32 v99, v111, v220, vcc
	v_cmp_lt_i32_e32 vcc, v105, v232
	v_cmp_gt_i32_e64 s[0:1], v105, v228
	s_or_b64 vcc, vcc, s[0:1]
	v_add_u32_e32 v105, 0xffffffa2, v1
	v_cndmask_b32_e32 v100, v100, v220, vcc
	v_cmp_lt_i32_e32 vcc, v105, v232
	v_cmp_gt_i32_e64 s[0:1], v105, v228
	s_or_b64 vcc, vcc, s[0:1]
	v_add_u32_e32 v105, 0xffffffa3, v1
	v_cndmask_b32_e32 v101, v101, v220, vcc
	v_cmp_lt_i32_e32 vcc, v105, v232
	v_cmp_gt_i32_e64 s[0:1], v105, v228
	s_or_b64 vcc, vcc, s[0:1]
	v_add_u32_e32 v105, 0xffffffa4, v1
	v_cndmask_b32_e32 v102, v102, v220, vcc
	v_cmp_lt_i32_e32 vcc, v105, v232
	v_cmp_gt_i32_e64 s[0:1], v105, v228
	s_or_b64 vcc, vcc, s[0:1]
	v_add_u32_e32 v105, 0xffffffb1, v1
	v_cndmask_b32_e32 v103, v103, v220, vcc
	v_cmp_lt_i32_e32 vcc, v105, v232
	v_cmp_gt_i32_e64 s[0:1], v105, v228
	s_or_b64 vcc, vcc, s[0:1]
	v_add_u32_e32 v105, 0xffffffb2, v1
	v_cndmask_b32_e32 v92, v92, v220, vcc
	v_cmp_lt_i32_e32 vcc, v105, v232
	v_cmp_gt_i32_e64 s[0:1], v105, v228
	s_or_b64 vcc, vcc, s[0:1]
	v_add_u32_e32 v105, 0xffffffb3, v1
	v_cndmask_b32_e32 v93, v93, v220, vcc
	v_cmp_lt_i32_e32 vcc, v105, v232
	v_cmp_gt_i32_e64 s[0:1], v105, v228
	s_or_b64 vcc, vcc, s[0:1]
	v_add_u32_e32 v1, 0xffffffb4, v1
	v_cndmask_b32_e32 v94, v94, v220, vcc
	v_cmp_lt_i32_e32 vcc, v1, v232
	v_cmp_gt_i32_e64 s[0:1], v1, v228
	s_or_b64 vcc, vcc, s[0:1]
	v_cndmask_b32_e32 v1, v95, v220, vcc
	v_max_f32_e32 v95, v3, v2
	v_max_f32_e32 v105, v112, v104
	v_max_f32_e32 v106, v98, v99
	v_max3_f32 v106, v96, v97, v106
	v_max3_f32 v95, v95, v105, v106
	v_max_f32_e32 v105, v102, v103
	v_max_f32_e32 v106, v94, v1
	v_max3_f32 v105, v100, v101, v105
	v_max3_f32 v106, v92, v93, v106
	v_max3_f32 v95, v95, v105, v106
	v_mov_b32_e32 v105, v95
	v_cmp_lt_f32_e32 vcc, s83, v3
	s_nop 1
	v_permlane16_swap_b32_e32 v95, v105
	v_max_f32_e32 v95, v95, v105
	v_mov_b32_e32 v105, v95
	s_nop 1
	v_permlane32_swap_b32_e32 v95, v105
	v_max3_f32 v105, v235, v95, v105
	v_sub_f32_e32 v95, v3, v105
	v_exp_f32_e32 v95, v95
	v_sub_f32_e32 v107, v2, v105
	v_exp_f32_e32 v107, v107
	v_sub_f32_e32 v108, v112, v105
	v_exp_f32_e32 v108, v108
	v_cndmask_b32_e32 v3, 0, v95, vcc
	v_cmp_lt_f32_e32 vcc, s83, v2
	v_sub_f32_e32 v109, v96, v105
	v_exp_f32_e32 v109, v109
	v_cndmask_b32_e32 v2, 0, v107, vcc
	v_cmp_lt_f32_e32 vcc, s83, v112
	v_add_f32_e32 v95, 0, v3
	v_add_f32_e32 v95, v2, v95
	v_cndmask_b32_e32 v107, 0, v108, vcc
	v_sub_f32_e32 v108, v104, v105
	v_exp_f32_e32 v108, v108
	v_cmp_lt_f32_e32 vcc, s83, v104
	v_add_f32_e32 v95, v107, v95
	v_sub_f32_e32 v106, v235, v105
	v_cndmask_b32_e32 v104, 0, v108, vcc
	v_cmp_lt_f32_e32 vcc, s83, v96
	v_sub_f32_e32 v96, v97, v105
	v_exp_f32_e32 v96, v96
	v_cndmask_b32_e32 v108, 0, v109, vcc
	v_sub_f32_e32 v109, v98, v105
	v_cmp_lt_f32_e32 vcc, s83, v97
	v_exp_f32_e32 v109, v109
	v_add_f32_e32 v95, v104, v95
	v_cndmask_b32_e32 v97, 0, v96, vcc
	v_sub_f32_e32 v96, v99, v105
	v_exp_f32_e32 v96, v96
	v_add_f32_e32 v95, v108, v95
	v_cmp_lt_f32_e32 vcc, s83, v98
	v_add_f32_e32 v95, v97, v95
	v_mov_b32_e32 v235, v105
	v_cndmask_b32_e32 v98, 0, v109, vcc
	v_cmp_lt_f32_e32 vcc, s83, v99
	v_add_f32_e32 v95, v98, v95
	v_sub_f32_e32 v109, v100, v105
	v_cndmask_b32_e32 v99, 0, v96, vcc
	v_exp_f32_e32 v109, v109
	v_add_f32_e32 v110, v99, v95
	v_sub_f32_e32 v95, v101, v105
	v_exp_f32_e32 v95, v95
	v_sub_f32_e32 v96, v102, v105
	v_cmp_lt_f32_e32 vcc, s83, v100
	v_exp_f32_e32 v96, v96
	s_nop 0
	v_cndmask_b32_e32 v100, 0, v109, vcc
	v_cmp_lt_f32_e32 vcc, s83, v101
	s_nop 1
	v_cndmask_b32_e32 v101, 0, v95, vcc
	v_sub_f32_e32 v95, v103, v105
	v_cmp_lt_f32_e32 vcc, s83, v102
	v_exp_f32_e32 v95, v95
	s_nop 0
	v_cndmask_b32_e32 v102, 0, v96, vcc
	v_sub_f32_e32 v96, v92, v105
	v_exp_f32_e32 v96, v96
	v_cmp_lt_f32_e32 vcc, s83, v103
	s_nop 1
	v_cndmask_b32_e32 v103, 0, v95, vcc
	v_cmp_lt_f32_e32 vcc, s83, v92
	v_sub_f32_e32 v92, v93, v105
	v_exp_f32_e32 v92, v92
	v_sub_f32_e32 v95, v94, v105
	v_cndmask_b32_e32 v109, 0, v96, vcc
	v_exp_f32_e32 v95, v95
	v_exp_f32_e32 v96, v106
	v_cmp_lt_f32_e32 vcc, s83, v93
	v_cvt_pk_bf16_f32 v93, v107, v104
	v_pk_mul_f32 v[22:23], v[22:23], v[96:97] op_sel_hi:[1,0]
	v_cndmask_b32_e32 v106, 0, v92, vcc
	v_cmp_lt_f32_e32 vcc, s83, v94
	v_cvt_pk_bf16_f32 v92, v3, v2
	v_cvt_pk_bf16_f32 v94, v108, v97
	v_cndmask_b32_e32 v111, 0, v95, vcc
	v_cvt_pk_bf16_f32 v95, v98, v99
	v_sub_f32_e32 v2, v1, v105
	v_pk_mul_f32 v[20:21], v[20:21], v[96:97] op_sel_hi:[1,0]
	v_pk_mul_f32 v[6:7], v[6:7], v[96:97] op_sel_hi:[1,0]
	v_pk_mul_f32 v[4:5], v[4:5], v[96:97] op_sel_hi:[1,0]
	v_mfma_f32_16x16x32_bf16 v[20:23], v[52:55], v[92:95], v[20:23]
	v_exp_f32_e32 v52, v2
	v_pk_mul_f32 v[46:47], v[46:47], v[96:97] op_sel_hi:[1,0]
	v_pk_mul_f32 v[44:45], v[44:45], v[96:97] op_sel_hi:[1,0]
	v_mfma_f32_16x16x32_bf16 v[2:5], v[48:51], v[92:95], v[4:7]
	v_mul_f32_e64 v10, v10, v96
	v_mul_f32_e64 v11, v11, v96
	v_pk_mul_f32 v[8:9], v[8:9], v[96:97] op_sel_hi:[1,0]
	v_cmp_lt_f32_e32 vcc, s83, v1
	v_add_f32_e32 v6, v100, v110
	v_mfma_f32_16x16x32_bf16 v[44:47], v[56:59], v[92:95], v[44:47]
	v_add_f32_e32 v6, v101, v6
	v_add_f32_e32 v6, v102, v6
	v_cndmask_b32_e32 v1, 0, v52, vcc
	v_mfma_f32_16x16x32_bf16 v[8:11], v[40:43], v[92:95], v[8:11]
	v_add_f32_e32 v6, v103, v6
	v_cvt_pk_bf16_f32 v40, v100, v101
	v_cvt_pk_bf16_f32 v41, v102, v103
	v_cvt_pk_bf16_f32 v42, v109, v106
	v_cvt_pk_bf16_f32 v43, v111, v1
	v_add_f32_e32 v6, v109, v6
	s_nop 0
	v_mfma_f32_16x16x32_bf16 v[44:47], v[36:39], v[40:43], v[44:47]
	v_mfma_f32_16x16x32_bf16 v[20:23], v[32:35], v[40:43], v[20:23]
	v_add_f32_e32 v32, v106, v6
	v_mfma_f32_16x16x32_bf16 v[4:7], v[28:31], v[40:43], v[2:5]
	v_mfma_f32_16x16x32_bf16 v[8:11], v[24:27], v[40:43], v[8:11]
	s_nop 1
	v_add_f32_e32 v2, v111, v32
	v_add_f32_e32 v234, v1, v2
	v_fmac_f32_e32 v234, v236, v96
